# streaming cache policy extended: nt on P8's x/y loads (last use), P5 f32 weight loads (single use), P13 X1/Y1 loads and output stores
# speedup vs baseline: 1.0019x; 1.0001x over previous
; __device__ __forceinline__ int src_col(int mat, int c) {
;     ...
;     if (mat == 2) {
;         if (c < CW) return CW + c;
;         const int cc = c - CW, tile = cc >> 8, w = cc & 255;
;         return w < 128 ? (tile * 128 + w) : (2 * CW + tile * 128 + (w - 128));
;     }
; __device__ __forceinline__ void tr_load_nc(const float* W, int N, int mat, int item, int lane, int nblk, float (&x)[32]) {
;     const int kb = item / nblk, nb = item % nblk, k0 = 64 * kb, n0 = 32 * nb;
;     const int sc = src_col(mat, n0 + (lane & 31));
;     const float* wp = W + (size_t)(k0 + (lane >> 5)) * N + sc;
; #pragma unroll
;     for (int i = 0; i < 32; ++i) x[i] = wp[(size_t)(2 * i) * N];
; }
; __global__ void __launch_bounds__(NTHREADS, 2) fwd(Args a) {
;     ...
;             ldi(j, x); ldi(j + jst, xn);
.LBB0_670:
	s_andn2_saveexec_b64 s[0:1], s[0:1]
	v_add_u32_e32 v2, 0x3000, v3
	s_or_b64 exec, exec, s[0:1]
	v_readlane_b32 s76, v254, 2
	v_lshrrev_b32_e32 v7, 5, v1
	v_readlane_b32 s84, v254, 10
	v_readlane_b32 s85, v254, 11
	v_lshl_or_b32 v3, s6, 6, v7
	s_mov_b32 s0, 0x24000
	v_mov_b64_e32 v[4:5], s[84:85]
	v_mad_i64_i32 v[4:5], s[0:1], v3, s0, v[4:5]
	v_ashrrev_i32_e32 v3, 31, v2
	v_lshl_add_u64 v[2:3], v[2:3], 2, v[4:5]
	v_add_co_u32_e32 v4, vcc, 0x48000, v2
	s_lshl_b32 s8, s16, 3
	s_nop 0
	v_addc_co_u32_e32 v5, vcc, 0, v3, vcc
	v_add_co_u32_e32 v12, vcc, 0x90000, v2
	s_add_i32 s6, s10, s8
	s_nop 0
	v_addc_co_u32_e32 v13, vcc, 0, v3, vcc
	v_add_co_u32_e32 v14, vcc, 0xd8000, v2
	s_min_i32 s0, s6, 0x6fff
	s_nop 0
	v_addc_co_u32_e32 v15, vcc, 0, v3, vcc
	v_add_co_u32_e32 v16, vcc, 0x120000, v2
	s_mul_hi_i32 s1, s0, 0x38e38e39
	s_nop 0
	v_addc_co_u32_e32 v17, vcc, 0, v3, vcc
	v_add_co_u32_e32 v18, vcc, 0x168000, v2
	s_lshr_b32 s4, s1, 31
	s_nop 0
	v_addc_co_u32_e32 v19, vcc, 0, v3, vcc
	v_add_co_u32_e32 v20, vcc, 0x1b0000, v2
	s_ashr_i32 s7, s1, 8
	s_nop 0
	v_addc_co_u32_e32 v21, vcc, 0, v3, vcc
	v_add_co_u32_e32 v22, vcc, 0x1f8000, v2
	s_add_i32 s7, s7, s4
	s_nop 0
	v_addc_co_u32_e32 v23, vcc, 0, v3, vcc
	global_load_dword v8, v[2:3], off nt
	global_load_dword v11, v[4:5], off nt
	global_load_dword v10, v[12:13], off nt
	s_nop 0
	global_load_dword v14, v[14:15], off nt
	s_nop 0
	global_load_dword v9, v[16:17], off nt
	global_load_dword v13, v[18:19], off nt
	global_load_dword v12, v[20:21], off nt
	global_load_dword v15, v[22:23], off nt
	v_add_co_u32_e32 v4, vcc, 0x240000, v2
	s_mul_i32 s1, s7, 0x480
	s_nop 0
	v_addc_co_u32_e32 v5, vcc, 0, v3, vcc
	v_add_co_u32_e32 v18, vcc, 0x288000, v2
	s_sub_i32 s0, s0, s1
	s_nop 0
	v_addc_co_u32_e32 v19, vcc, 0, v3, vcc
	v_add_co_u32_e32 v20, vcc, 0x2d0000, v2
	s_lshl_b32 s4, s0, 5
	s_nop 0
	v_addc_co_u32_e32 v21, vcc, 0, v3, vcc
	v_add_co_u32_e32 v22, vcc, 0x318000, v2
	s_movk_i32 s0, 0x2fff
	s_nop 0
	v_addc_co_u32_e32 v23, vcc, 0, v3, vcc
	v_add_co_u32_e32 v24, vcc, 0x360000, v2
	v_readlane_b32 s77, v254, 3
	s_nop 0
	v_addc_co_u32_e32 v25, vcc, 0, v3, vcc
	v_add_co_u32_e32 v26, vcc, 0x3a8000, v2
	v_readlane_b32 s78, v254, 4
	s_nop 0
	v_addc_co_u32_e32 v27, vcc, 0, v3, vcc
	v_add_co_u32_e32 v28, vcc, 0x3f0000, v2
	v_readlane_b32 s79, v254, 5
	s_nop 0
	v_addc_co_u32_e32 v29, vcc, 0, v3, vcc
	v_add_co_u32_e32 v30, vcc, 0x438000, v2
	v_readlane_b32 s80, v254, 6
	s_nop 0
	v_addc_co_u32_e32 v31, vcc, 0, v3, vcc
	global_load_dword v16, v[4:5], off nt
	s_nop 0
	global_load_dword v19, v[18:19], off nt
	s_nop 0
	global_load_dword v18, v[20:21], off nt
	s_nop 0
	global_load_dword v22, v[22:23], off nt
	s_nop 0
	global_load_dword v17, v[24:25], off nt
	global_load_dword v21, v[26:27], off nt
	global_load_dword v20, v[28:29], off nt
	global_load_dword v23, v[30:31], off nt
	v_add_co_u32_e32 v4, vcc, 0x480000, v2
	v_readlane_b32 s81, v254, 7
	s_nop 0
	v_addc_co_u32_e32 v5, vcc, 0, v3, vcc
	v_add_co_u32_e32 v24, vcc, 0x4c8000, v2
	v_readlane_b32 s82, v254, 8
	s_nop 0
	v_addc_co_u32_e32 v25, vcc, 0, v3, vcc
	v_add_co_u32_e32 v26, vcc, 0x510000, v2
	v_readlane_b32 s83, v254, 9
	s_nop 0
	v_addc_co_u32_e32 v27, vcc, 0, v3, vcc
	v_add_co_u32_e32 v28, vcc, 0x558000, v2
	v_readlane_b32 s86, v254, 12
	s_nop 0
	v_addc_co_u32_e32 v29, vcc, 0, v3, vcc
	v_add_co_u32_e32 v30, vcc, 0x5a0000, v2
	v_readlane_b32 s87, v254, 13
	s_nop 0
	v_addc_co_u32_e32 v31, vcc, 0, v3, vcc
	v_add_co_u32_e32 v36, vcc, 0x5e8000, v2
	v_readlane_b32 s88, v254, 14
	s_nop 0
	v_addc_co_u32_e32 v37, vcc, 0, v3, vcc
	v_add_co_u32_e32 v40, vcc, 0x630000, v2
	v_readlane_b32 s89, v254, 15
	s_nop 0
	v_addc_co_u32_e32 v41, vcc, 0, v3, vcc
	v_add_co_u32_e32 v42, vcc, 0x678000, v2
	v_readlane_b32 s90, v254, 16
	s_nop 0
	v_addc_co_u32_e32 v43, vcc, 0, v3, vcc
	global_load_dword v32, v[4:5], off nt
	global_load_dword v35, v[24:25], off nt
	global_load_dword v34, v[26:27], off nt
	global_load_dword v38, v[28:29], off nt
	global_load_dword v33, v[30:31], off nt
	s_nop 0
	global_load_dword v37, v[36:37], off nt
	s_nop 0
	global_load_dword v36, v[40:41], off nt
	global_load_dword v39, v[42:43], off nt
	v_add_co_u32_e32 v4, vcc, 0x6c0000, v2
	v_readlane_b32 s91, v254, 17
	s_nop 0
	v_addc_co_u32_e32 v5, vcc, 0, v3, vcc
	v_add_co_u32_e32 v24, vcc, 0x708000, v2
	s_nop 1
	v_addc_co_u32_e32 v25, vcc, 0, v3, vcc
	v_add_co_u32_e32 v26, vcc, 0x750000, v2
	s_nop 1
	v_addc_co_u32_e32 v27, vcc, 0, v3, vcc
	v_add_co_u32_e32 v28, vcc, 0x798000, v2
	s_nop 1
	v_addc_co_u32_e32 v29, vcc, 0, v3, vcc
	v_add_co_u32_e32 v30, vcc, 0x7e0000, v2
	s_nop 1
	v_addc_co_u32_e32 v31, vcc, 0, v3, vcc
	v_add_co_u32_e32 v40, vcc, 0x828000, v2
	s_nop 1
	v_addc_co_u32_e32 v41, vcc, 0, v3, vcc
	v_add_co_u32_e32 v42, vcc, 0x870000, v2
	s_nop 1
	v_addc_co_u32_e32 v43, vcc, 0, v3, vcc
	v_add_co_u32_e32 v2, vcc, 0x8b8000, v2
	s_nop 1
	v_addc_co_u32_e32 v3, vcc, 0, v3, vcc
	global_load_dword v48, v[4:5], off nt
	global_load_dword v51, v[24:25], off nt
	global_load_dword v50, v[26:27], off nt
	global_load_dword v54, v[28:29], off nt
	global_load_dword v49, v[30:31], off nt
	global_load_dword v53, v[40:41], off nt
	global_load_dword v52, v[42:43], off nt
	global_load_dword v55, v[2:3], off nt
	v_or_b32_e32 v3, s4, v6
	v_cmp_lt_i32_e32 vcc, s0, v3
	s_and_saveexec_b64 s[0:1], vcc
	s_xor_b64 s[0:1], exec, s[0:1]
	s_cbranch_execz .LBB0_678
	s_add_i32 s9, s4, 0xffffd000
	s_movk_i32 s4, 0x7f
	s_lshr_b32 s9, s9, 1
	v_cmp_gt_u32_sdwa s[4:5], v3, s4 src0_sel:BYTE_0 src1_sel:DWORD
	s_and_b32 s9, s9, 0x7fffff80
	s_and_saveexec_b64 s[12:13], s[4:5]
	s_xor_b64 s[4:5], exec, s[12:13]
	v_add_u32_sdwa v2, v3, s9 dst_sel:DWORD dst_unused:UNUSED_PAD src0_sel:BYTE_0 src1_sel:DWORD
	v_add_u32_e32 v2, 0x5f80, v2
	s_andn2_saveexec_b64 s[4:5], s[4:5]
	v_or_b32_sdwa v2, s9, v3 dst_sel:DWORD dst_unused:UNUSED_PAD src0_sel:DWORD src1_sel:BYTE_0
	s_or_b64 exec, exec, s[4:5]
; __device__ __forceinline__ void tr_load_nc(const float* W, int N, int mat, int item, int lane, int nblk, float (&x)[32]) {
;     const int kb = item / nblk, nb = item % nblk, k0 = 64 * kb, n0 = 32 * nb;
;     const int sc = src_col(mat, n0 + (lane & 31));
;     const float* wp = W + (size_t)(k0 + (lane >> 5)) * N + sc;
; #pragma unroll
;     for (int i = 0; i < 32; ++i) x[i] = wp[(size_t)(2 * i) * N];
; }
; __global__ void __launch_bounds__(NTHREADS, 2) fwd(Args a) {
;     ...
;             ldi(j, x); ldi(j + jst, xn);
;             while (j + 2 * jst < L1_P5) {
.LBB0_678:
	s_andn2_saveexec_b64 s[0:1], s[0:1]
	v_add_u32_e32 v2, 0x3000, v3
	s_or_b64 exec, exec, s[0:1]
	v_readlane_b32 s76, v254, 2
	v_readlane_b32 s84, v254, 10
	v_readlane_b32 s85, v254, 11
	v_lshl_or_b32 v3, s7, 6, v7
	s_mov_b32 s11, 0x24000
	v_mov_b64_e32 v[4:5], s[84:85]
	v_mad_i64_i32 v[4:5], s[0:1], v3, s11, v[4:5]
	v_ashrrev_i32_e32 v3, 31, v2
	v_lshl_add_u64 v[2:3], v[2:3], 2, v[4:5]
	v_add_co_u32_e32 v4, vcc, 0x48000, v2
	s_lshl_b32 s0, s17, 14
	s_nop 0
	v_addc_co_u32_e32 v5, vcc, 0, v3, vcc
	v_add_co_u32_e32 v28, vcc, 0x90000, v2
	s_add_i32 s9, s0, 0
	s_nop 0
	v_addc_co_u32_e32 v29, vcc, 0, v3, vcc
	v_add_co_u32_e32 v30, vcc, 0xd8000, v2
	s_add_i32 s0, s6, s8
	s_nop 0
	v_addc_co_u32_e32 v31, vcc, 0, v3, vcc
	v_add_co_u32_e32 v40, vcc, 0x120000, v2
	s_cmpk_gt_i32 s0, 0x6fff
	s_nop 0
	v_addc_co_u32_e32 v41, vcc, 0, v3, vcc
	v_add_co_u32_e32 v42, vcc, 0x168000, v2
	v_readlane_b32 s77, v254, 3
	s_nop 0
	v_addc_co_u32_e32 v43, vcc, 0, v3, vcc
	v_add_co_u32_e32 v44, vcc, 0x1b0000, v2
	v_readlane_b32 s78, v254, 4
	s_nop 0
	v_addc_co_u32_e32 v45, vcc, 0, v3, vcc
	v_add_co_u32_e32 v46, vcc, 0x1f8000, v2
	v_readlane_b32 s79, v254, 5
	s_nop 0
	v_addc_co_u32_e32 v47, vcc, 0, v3, vcc
	global_load_dword v24, v[2:3], off nt
	global_load_dword v26, v[4:5], off nt
	global_load_dword v25, v[28:29], off nt
	s_nop 0
	global_load_dword v28, v[30:31], off nt
	global_load_dword v27, v[40:41], off nt
	s_nop 0
	global_load_dword v30, v[42:43], off nt
	global_load_dword v29, v[44:45], off nt
	global_load_dword v31, v[46:47], off nt
	v_add_co_u32_e32 v4, vcc, 0x240000, v2
	v_readlane_b32 s80, v254, 6
	s_nop 0
	v_addc_co_u32_e32 v5, vcc, 0, v3, vcc
	v_add_co_u32_e32 v42, vcc, 0x288000, v2
	v_readlane_b32 s81, v254, 7
	s_nop 0
	v_addc_co_u32_e32 v43, vcc, 0, v3, vcc
	v_add_co_u32_e32 v44, vcc, 0x2d0000, v2
	v_readlane_b32 s82, v254, 8
	s_nop 0
	v_addc_co_u32_e32 v45, vcc, 0, v3, vcc
	v_add_co_u32_e32 v46, vcc, 0x318000, v2
	v_readlane_b32 s83, v254, 9
	s_nop 0
	v_addc_co_u32_e32 v47, vcc, 0, v3, vcc
	v_add_co_u32_e32 v56, vcc, 0x360000, v2
	v_readlane_b32 s86, v254, 12
	s_nop 0
	v_addc_co_u32_e32 v57, vcc, 0, v3, vcc
	v_add_co_u32_e32 v58, vcc, 0x3a8000, v2
	v_readlane_b32 s87, v254, 13
	s_nop 0
	v_addc_co_u32_e32 v59, vcc, 0, v3, vcc
	v_add_co_u32_e32 v60, vcc, 0x3f0000, v2
	v_readlane_b32 s88, v254, 14
	s_nop 0
	v_addc_co_u32_e32 v61, vcc, 0, v3, vcc
	v_add_co_u32_e32 v62, vcc, 0x438000, v2
	v_readlane_b32 s89, v254, 15
	s_nop 0
	v_addc_co_u32_e32 v63, vcc, 0, v3, vcc
	global_load_dword v40, v[4:5], off nt
	s_nop 0
	global_load_dword v42, v[42:43], off nt
	s_nop 0
	global_load_dword v41, v[44:45], off nt
	s_nop 0
	global_load_dword v44, v[46:47], off nt
	global_load_dword v43, v[56:57], off nt
	s_nop 0
	global_load_dword v46, v[58:59], off nt
	global_load_dword v45, v[60:61], off nt
	global_load_dword v47, v[62:63], off nt
	v_add_co_u32_e32 v4, vcc, 0x480000, v2
	v_readlane_b32 s90, v254, 16
	s_nop 0
	v_addc_co_u32_e32 v5, vcc, 0, v3, vcc
	v_add_co_u32_e32 v58, vcc, 0x4c8000, v2
	v_readlane_b32 s91, v254, 17
	s_nop 0
	v_addc_co_u32_e32 v59, vcc, 0, v3, vcc
	v_add_co_u32_e32 v60, vcc, 0x510000, v2
	s_nop 1
	v_addc_co_u32_e32 v61, vcc, 0, v3, vcc
	v_add_co_u32_e32 v62, vcc, 0x558000, v2
	s_nop 1
	v_addc_co_u32_e32 v63, vcc, 0, v3, vcc
	v_add_co_u32_e32 v64, vcc, 0x5a0000, v2
	s_nop 1
	v_addc_co_u32_e32 v65, vcc, 0, v3, vcc
	v_add_co_u32_e32 v66, vcc, 0x5e8000, v2
	s_nop 1
	v_addc_co_u32_e32 v67, vcc, 0, v3, vcc
	v_add_co_u32_e32 v68, vcc, 0x630000, v2
	s_nop 1
	v_addc_co_u32_e32 v69, vcc, 0, v3, vcc
	v_add_co_u32_e32 v70, vcc, 0x678000, v2
	s_nop 1
	v_addc_co_u32_e32 v71, vcc, 0, v3, vcc
	global_load_dword v56, v[4:5], off nt
	s_nop 0
	global_load_dword v58, v[58:59], off nt
	s_nop 0
	global_load_dword v57, v[60:61], off nt
	s_nop 0
	global_load_dword v60, v[62:63], off nt
	global_load_dword v59, v[64:65], off nt
	s_nop 0
	global_load_dword v62, v[66:67], off nt
	global_load_dword v61, v[68:69], off nt
	global_load_dword v63, v[70:71], off nt
	v_add_co_u32_e32 v4, vcc, 0x6c0000, v2
	s_nop 1
	v_addc_co_u32_e32 v5, vcc, 0, v3, vcc
	v_add_co_u32_e32 v66, vcc, 0x708000, v2
	s_nop 1
	v_addc_co_u32_e32 v67, vcc, 0, v3, vcc
	v_add_co_u32_e32 v68, vcc, 0x750000, v2
	s_nop 1
	v_addc_co_u32_e32 v69, vcc, 0, v3, vcc
	v_add_co_u32_e32 v70, vcc, 0x798000, v2
	s_nop 1
	v_addc_co_u32_e32 v71, vcc, 0, v3, vcc
	v_add_co_u32_e32 v72, vcc, 0x7e0000, v2
	s_nop 1
	v_addc_co_u32_e32 v73, vcc, 0, v3, vcc
	v_add_co_u32_e32 v74, vcc, 0x828000, v2
	s_nop 1
	v_addc_co_u32_e32 v75, vcc, 0, v3, vcc
	v_add_co_u32_e32 v76, vcc, 0x870000, v2
	s_nop 1
	v_addc_co_u32_e32 v77, vcc, 0, v3, vcc
	v_add_co_u32_e32 v2, vcc, 0x8b8000, v2
	s_nop 1
	v_addc_co_u32_e32 v3, vcc, 0, v3, vcc
	global_load_dword v64, v[4:5], off nt
	s_nop 0
	global_load_dword v67, v[66:67], off nt
	s_nop 0
	global_load_dword v66, v[68:69], off nt
	s_nop 0
	global_load_dword v70, v[70:71], off nt
	s_nop 0
	global_load_dword v69, v[72:73], off nt
	s_nop 0
	global_load_dword v72, v[74:75], off nt
	global_load_dword v71, v[76:77], off nt
	global_load_dword v73, v[2:3], off nt
	s_cbranch_scc1 .LBB0_707
	v_lshlrev_b32_e32 v2, 2, v6
	v_mul_u32_u24_e32 v3, 0x84, v7
	v_add3_u32 v65, s9, v2, v3
	v_lshlrev_b32_e32 v2, 3, v1
	v_lshrrev_b32_e32 v68, 3, v1
	v_and_b32_e32 v2, 56, v2
	s_lshl_b32 s12, s16, 4
	s_mul_i32 s13, s16, 24
	v_mul_u32_u24_e32 v4, 0x84, v2
	v_lshlrev_b32_e32 v2, 1, v2
	v_mov_b32_e32 v3, 0
	v_lshlrev_b32_e32 v5, 2, v68
	v_lshl_add_u64 v[2:3], s[92:93], 0, v[2:3]
	v_add3_u32 v74, s9, v4, v5
	v_or_b32_e32 v75, 8, v68
	v_or_b32_e32 v76, 16, v68
	v_or_b32_e32 v77, 24, v68
	v_lshl_or_b32 v78, s10, 5, v68
	s_lshl_b32 s14, s13, 5
	s_sub_i32 s15, s13, s12
	s_add_i32 s16, s13, s8
	s_movk_i32 s17, 0x2fff
	s_movk_i32 s18, 0x7f
	s_branch .LBB0_683
; __device__ __forceinline__ void tr_load_nc(const float* W, int N, int mat, int item, int lane, int nblk, float (&x)[32]) {
;     const int kb = item / nblk, nb = item % nblk, k0 = 64 * kb, n0 = 32 * nb;
;     const int sc = src_col(mat, n0 + (lane & 31));
;     const float* wp = W + (size_t)(k0 + (lane >> 5)) * N + sc;
; #pragma unroll
;     for (int i = 0; i < 32; ++i) x[i] = wp[(size_t)(2 * i) * N];
; }
; __global__ void __launch_bounds__(NTHREADS, 2) fwd(Args a) {
;     ...
;                 ldi(j + 2 * jst, xc); sti(j, x);
;                 ldi(j + 3 * jst, x);  sti(j + jst, xn);
;                 ldi(j + 4 * jst, xn); sti(j + 2 * jst, xc);
.LBB0_682:
	s_or_b64 exec, exec, s[4:5]
	v_readlane_b32 s76, v254, 2
	v_readlane_b32 s84, v254, 10
	v_readlane_b32 s85, v254, 11
	v_lshl_or_b32 v5, s1, 6, v7
	s_ashr_i32 s1, s0, 31
	v_mov_b64_e32 v[24:25], s[84:85]
	v_mad_i64_i32 v[24:25], s[4:5], v5, s11, v[24:25]
	v_ashrrev_i32_e32 v5, 31, v4
	v_lshl_add_u64 v[4:5], v[4:5], 2, v[24:25]
	v_add_co_u32_e32 v26, vcc, 0x48000, v4
	v_add_u32_e32 v78, s14, v78
	s_nop 0
	v_addc_co_u32_e32 v27, vcc, 0, v5, vcc
	v_add_co_u32_e32 v28, vcc, 0x90000, v4
	v_readlane_b32 s77, v254, 3
	s_nop 0
	v_addc_co_u32_e32 v29, vcc, 0, v5, vcc
	v_add_co_u32_e32 v30, vcc, 0xd8000, v4
	v_readlane_b32 s78, v254, 4
	s_nop 0
	v_addc_co_u32_e32 v31, vcc, 0, v5, vcc
	v_add_co_u32_e32 v40, vcc, 0x120000, v4
	v_readlane_b32 s79, v254, 5
	s_nop 0
	v_addc_co_u32_e32 v41, vcc, 0, v5, vcc
	v_add_co_u32_e32 v42, vcc, 0x168000, v4
	v_readlane_b32 s80, v254, 6
	s_nop 0
	v_addc_co_u32_e32 v43, vcc, 0, v5, vcc
	v_add_co_u32_e32 v44, vcc, 0x1b0000, v4
	v_readlane_b32 s81, v254, 7
	s_nop 0
	v_addc_co_u32_e32 v45, vcc, 0, v5, vcc
	v_add_co_u32_e32 v46, vcc, 0x1f8000, v4
	v_readlane_b32 s82, v254, 8
	s_nop 0
	v_addc_co_u32_e32 v47, vcc, 0, v5, vcc
	global_load_dword v24, v[4:5], off nt
	s_nop 0
	global_load_dword v26, v[26:27], off nt
	s_nop 0
	global_load_dword v25, v[28:29], off nt
	s_nop 0
	global_load_dword v28, v[30:31], off nt
	global_load_dword v27, v[40:41], off nt
	s_nop 0
	global_load_dword v30, v[42:43], off nt
	global_load_dword v29, v[44:45], off nt
	global_load_dword v31, v[46:47], off nt
	v_add_co_u32_e32 v40, vcc, 0x240000, v4
	v_readlane_b32 s83, v254, 9
	s_nop 0
	v_addc_co_u32_e32 v41, vcc, 0, v5, vcc
	v_add_co_u32_e32 v42, vcc, 0x288000, v4
	v_readlane_b32 s86, v254, 12
	s_nop 0
	v_addc_co_u32_e32 v43, vcc, 0, v5, vcc
	v_add_co_u32_e32 v44, vcc, 0x2d0000, v4
	v_readlane_b32 s87, v254, 13
	s_nop 0
	v_addc_co_u32_e32 v45, vcc, 0, v5, vcc
	v_add_co_u32_e32 v46, vcc, 0x318000, v4
	v_readlane_b32 s88, v254, 14
	s_nop 0
	v_addc_co_u32_e32 v47, vcc, 0, v5, vcc
	v_add_co_u32_e32 v56, vcc, 0x360000, v4
	v_readlane_b32 s89, v254, 15
	s_nop 0
	v_addc_co_u32_e32 v57, vcc, 0, v5, vcc
	v_add_co_u32_e32 v58, vcc, 0x3a8000, v4
	v_readlane_b32 s90, v254, 16
	s_nop 0
	v_addc_co_u32_e32 v59, vcc, 0, v5, vcc
	v_add_co_u32_e32 v60, vcc, 0x3f0000, v4
	v_readlane_b32 s91, v254, 17
	s_nop 0
	v_addc_co_u32_e32 v61, vcc, 0, v5, vcc
	v_add_co_u32_e32 v62, vcc, 0x438000, v4
	s_nop 1
	v_addc_co_u32_e32 v63, vcc, 0, v5, vcc
	global_load_dword v40, v[40:41], off nt
	s_nop 0
	global_load_dword v42, v[42:43], off nt
	s_nop 0
	global_load_dword v41, v[44:45], off nt
	s_nop 0
	global_load_dword v44, v[46:47], off nt
	global_load_dword v43, v[56:57], off nt
	s_nop 0
	global_load_dword v46, v[58:59], off nt
	global_load_dword v45, v[60:61], off nt
	global_load_dword v47, v[62:63], off nt
	v_add_co_u32_e32 v56, vcc, 0x480000, v4
	s_nop 1
	v_addc_co_u32_e32 v57, vcc, 0, v5, vcc
	v_add_co_u32_e32 v58, vcc, 0x4c8000, v4
	s_nop 1
	v_addc_co_u32_e32 v59, vcc, 0, v5, vcc
	v_add_co_u32_e32 v60, vcc, 0x510000, v4
	s_nop 1
	v_addc_co_u32_e32 v61, vcc, 0, v5, vcc
	v_add_co_u32_e32 v62, vcc, 0x558000, v4
	s_nop 1
	v_addc_co_u32_e32 v63, vcc, 0, v5, vcc
	v_add_co_u32_e32 v66, vcc, 0x5a0000, v4
	s_nop 1
	v_addc_co_u32_e32 v67, vcc, 0, v5, vcc
	v_add_co_u32_e32 v70, vcc, 0x5e8000, v4
	s_nop 1
	v_addc_co_u32_e32 v71, vcc, 0, v5, vcc
	v_add_co_u32_e32 v72, vcc, 0x630000, v4
	s_nop 1
	v_addc_co_u32_e32 v73, vcc, 0, v5, vcc
	v_add_co_u32_e32 v118, vcc, 0x678000, v4
	s_nop 1
	v_addc_co_u32_e32 v119, vcc, 0, v5, vcc
	global_load_dword v56, v[56:57], off nt
	s_nop 0
	global_load_dword v58, v[58:59], off nt
	s_nop 0
	global_load_dword v57, v[60:61], off nt
	s_nop 0
	global_load_dword v60, v[62:63], off nt
	global_load_dword v59, v[66:67], off nt
	s_nop 0
	global_load_dword v62, v[70:71], off nt
	global_load_dword v61, v[72:73], off nt
	global_load_dword v63, v[118:119], off nt
	v_add_co_u32_e32 v66, vcc, 0x6c0000, v4
	s_nop 1
	v_addc_co_u32_e32 v67, vcc, 0, v5, vcc
	v_add_co_u32_e32 v70, vcc, 0x708000, v4
	s_nop 1
	v_addc_co_u32_e32 v71, vcc, 0, v5, vcc
	v_add_co_u32_e32 v72, vcc, 0x750000, v4
	s_nop 1
	v_addc_co_u32_e32 v73, vcc, 0, v5, vcc
	v_add_co_u32_e32 v118, vcc, 0x798000, v4
	s_nop 1
	v_addc_co_u32_e32 v119, vcc, 0, v5, vcc
	v_add_co_u32_e32 v120, vcc, 0x7e0000, v4
	s_nop 1
	v_addc_co_u32_e32 v121, vcc, 0, v5, vcc
	v_add_co_u32_e32 v122, vcc, 0x828000, v4
	s_nop 1
	v_addc_co_u32_e32 v123, vcc, 0, v5, vcc
	v_add_co_u32_e32 v124, vcc, 0x870000, v4
	s_nop 1
	v_addc_co_u32_e32 v125, vcc, 0, v5, vcc
	v_add_co_u32_e32 v4, vcc, 0x8b8000, v4
	s_nop 1
	v_addc_co_u32_e32 v5, vcc, 0, v5, vcc
	global_load_dword v64, v[66:67], off nt
	s_nop 0
	global_load_dword v67, v[70:71], off nt
	global_load_dword v66, v[72:73], off nt
	s_nop 0
	global_load_dword v70, v[118:119], off nt
	global_load_dword v69, v[120:121], off nt
	global_load_dword v72, v[122:123], off nt
	global_load_dword v71, v[124:125], off nt
	global_load_dword v73, v[4:5], off nt
	s_waitcnt vmcnt(63)
; #define GAS __attribute__((address_space(1)))
; #define LAS __attribute__((address_space(3)))
; #define LDS_WAIT() asm volatile("s_waitcnt lgkmcnt(0)" ::: "memory")
; __device__ __forceinline__ unsigned pk2(float lo, float hi) { return pg8::cvt_pk_bf16(lo, hi); }
; __device__ __forceinline__ void tr_store(bf16* WT, int K, LAS float* scr, int item, int lane, int nblk, const float (&x)[32]) {
;     const int kb = item / nblk, nb = item % nblk, k0 = 64 * kb, n0 = 32 * nb;
; #pragma unroll
;     for (int i = 0; i < 32; ++i) { const int kk = 2 * i + (lane >> 5); scr[kk * 33 + (lane & 31)] = x[i]; }
;     LDS_WAIT(); asm volatile("" ::: "memory");
;     const int c = lane & 7;
; #pragma unroll
;     for (int j = 0; j < 4; ++j) { const int n = (lane >> 3) + 8 * j; const LAS float* s = scr + (8 * c) * 33 + n;
;         v4u o; o.x = pk2(s[0 * 33], s[1 * 33]); o.y = pk2(s[2 * 33], s[3 * 33]); o.z = pk2(s[4 * 33], s[5 * 33]); o.w = pk2(s[6 * 33], s[7 * 33]);
;         *(GAS v4u*)(WT + (size_t)(n0 + n) * K + k0 + 8 * c) = o; }
;     LDS_WAIT(); asm volatile("" ::: "memory");
; __global__ void __launch_bounds__(NTHREADS, 2) fwd(Args a) {
;     ...
;             while (j + 2 * jst < L1_P5) {
	ds_write2_b32 v65, v79, v80 offset1:66
	ds_write2_b32 v65, v81, v82 offset0:132 offset1:198
	ds_write2_b32 v111, v83, v84 offset0:8 offset1:74
	ds_write2_b32 v111, v85, v86 offset0:140 offset1:206
	ds_write2_b32 v112, v87, v88 offset0:16 offset1:82
	ds_write2_b32 v112, v89, v90 offset0:148 offset1:214
	ds_write2_b32 v113, v91, v92 offset0:24 offset1:90
	ds_write2_b32 v113, v93, v94 offset0:156 offset1:222
	ds_write2_b32 v114, v95, v96 offset0:32 offset1:98
	ds_write2_b32 v114, v97, v98 offset0:164 offset1:230
	ds_write2_b32 v115, v99, v100 offset0:40 offset1:106
	ds_write2_b32 v115, v101, v102 offset0:172 offset1:238
	ds_write2_b32 v116, v103, v104 offset0:48 offset1:114
	ds_write2_b32 v116, v105, v106 offset0:180 offset1:246
	ds_write2_b32 v117, v107, v108 offset0:56 offset1:122
	ds_write2_b32 v117, v109, v110 offset0:188 offset1:254
	s_waitcnt lgkmcnt(0)
	ds_read2_b32 v[4:5], v74 offset1:33
	s_waitcnt lgkmcnt(0)
	v_cvt_pk_bf16_f32 v80, v4, v5
	ds_read2_b32 v[4:5], v74 offset0:66 offset1:99
	s_waitcnt lgkmcnt(0)
	v_cvt_pk_bf16_f32 v81, v4, v5
	ds_read2_b32 v[4:5], v74 offset0:132 offset1:165
	s_waitcnt lgkmcnt(0)
	v_cvt_pk_bf16_f32 v82, v4, v5
	ds_read2_b32 v[4:5], v74 offset0:198 offset1:231
	s_waitcnt lgkmcnt(0)
	v_cvt_pk_bf16_f32 v83, v4, v5
	v_or_b32_e32 v4, s19, v68
	v_ashrrev_i32_e32 v5, 31, v4
	v_lshl_add_u64 v[84:85], s[0:1], 1, v[2:3]
	v_lshlrev_b64 v[4:5], 13, v[4:5]
	v_lshl_add_u64 v[4:5], v[84:85], 0, v[4:5]
	ds_read2_b32 v[86:87], v74 offset0:8 offset1:41
	global_store_dwordx4 v[4:5], v[80:83], off
	s_add_i32 s0, s10, s12
	s_cmpk_lt_i32 s0, 0x7000
	s_waitcnt lgkmcnt(0)
	v_cvt_pk_bf16_f32 v80, v86, v87
	ds_read2_b32 v[4:5], v74 offset0:74 offset1:107
	s_waitcnt lgkmcnt(0)
	v_cvt_pk_bf16_f32 v81, v4, v5
	ds_read2_b32 v[4:5], v74 offset0:140 offset1:173
	s_waitcnt lgkmcnt(0)
	v_cvt_pk_bf16_f32 v82, v4, v5
	ds_read2_b32 v[4:5], v74 offset0:206 offset1:239
	s_waitcnt lgkmcnt(0)
	v_cvt_pk_bf16_f32 v83, v4, v5
	v_or_b32_e32 v4, s19, v75
	v_ashrrev_i32_e32 v5, 31, v4
	v_lshlrev_b64 v[4:5], 13, v[4:5]
	v_lshl_add_u64 v[4:5], v[84:85], 0, v[4:5]
	ds_read2_b32 v[86:87], v74 offset0:16 offset1:49
	global_store_dwordx4 v[4:5], v[80:83], off
	s_waitcnt lgkmcnt(0)
	s_nop 0
	v_cvt_pk_bf16_f32 v80, v86, v87
	ds_read2_b32 v[4:5], v74 offset0:82 offset1:115
	s_waitcnt lgkmcnt(0)
	v_cvt_pk_bf16_f32 v81, v4, v5
	ds_read2_b32 v[4:5], v74 offset0:148 offset1:181
	s_waitcnt lgkmcnt(0)
	v_cvt_pk_bf16_f32 v82, v4, v5
	ds_read2_b32 v[4:5], v74 offset0:214 offset1:247
	s_waitcnt lgkmcnt(0)
	v_cvt_pk_bf16_f32 v83, v4, v5
	v_or_b32_e32 v4, s19, v76
	v_ashrrev_i32_e32 v5, 31, v4
	v_lshlrev_b64 v[4:5], 13, v[4:5]
	v_lshl_add_u64 v[4:5], v[84:85], 0, v[4:5]
	ds_read2_b32 v[86:87], v74 offset0:24 offset1:57
	global_store_dwordx4 v[4:5], v[80:83], off
	s_waitcnt lgkmcnt(0)
	s_nop 0
	v_cvt_pk_bf16_f32 v80, v86, v87
	ds_read2_b32 v[4:5], v74 offset0:90 offset1:123
	s_waitcnt lgkmcnt(0)
	v_cvt_pk_bf16_f32 v81, v4, v5
	ds_read2_b32 v[4:5], v74 offset0:156 offset1:189
	s_waitcnt lgkmcnt(0)
	v_cvt_pk_bf16_f32 v82, v4, v5
	ds_read2_b32 v[4:5], v74 offset0:222 offset1:255
	s_waitcnt lgkmcnt(0)
	v_cvt_pk_bf16_f32 v83, v4, v5
	v_or_b32_e32 v4, s19, v77
	v_ashrrev_i32_e32 v5, 31, v4
	v_lshlrev_b64 v[4:5], 13, v[4:5]
	v_lshl_add_u64 v[4:5], v[84:85], 0, v[4:5]
	global_store_dwordx4 v[4:5], v[80:83], off
	s_waitcnt lgkmcnt(0)
	s_cbranch_scc0 .LBB0_707

; __device__ __forceinline__ void tr_load_nc(const float* W, int N, int mat, int item, int lane, int nblk, float (&x)[32]) {
;     const int kb = item / nblk, nb = item % nblk, k0 = 64 * kb, n0 = 32 * nb;
;     const int sc = src_col(mat, n0 + (lane & 31));
;     const float* wp = W + (size_t)(k0 + (lane >> 5)) * N + sc;
; #pragma unroll
;     for (int i = 0; i < 32; ++i) x[i] = wp[(size_t)(2 * i) * N];
; }
; __global__ void __launch_bounds__(NTHREADS, 2) fwd(Args a) {
;     ...
;                 ldi(j + 2 * jst, xc); sti(j, x);
;                 ldi(j + 3 * jst, x);  sti(j + jst, xn);
.LBB0_689:
	s_andn2_saveexec_b64 s[0:1], s[0:1]
	v_add_u32_e32 v4, 0x3000, v5
	s_or_b64 exec, exec, s[0:1]
	v_readlane_b32 s76, v254, 2
	s_lshl_b32 s0, s6, 6
	v_readlane_b32 s84, v254, 10
	v_readlane_b32 s85, v254, 11
	v_or_b32_e32 v5, s0, v7
	s_mul_hi_i32 s1, s20, 0x38e38e39
	v_mov_b64_e32 v[80:81], s[84:85]
	v_mad_i64_i32 v[80:81], s[4:5], v5, s11, v[80:81]
	v_ashrrev_i32_e32 v5, 31, v4
	v_lshl_add_u64 v[4:5], v[4:5], 2, v[80:81]
	v_add_co_u32_e32 v80, vcc, 0x48000, v4
	s_lshr_b32 s4, s1, 31
	s_nop 0
	v_addc_co_u32_e32 v81, vcc, 0, v5, vcc
	v_add_co_u32_e32 v82, vcc, 0x90000, v4
	s_ashr_i32 s1, s1, 8
	s_nop 0
	v_addc_co_u32_e32 v83, vcc, 0, v5, vcc
	v_add_co_u32_e32 v84, vcc, 0xd8000, v4
	s_add_i32 s1, s1, s4
	s_nop 0
	v_addc_co_u32_e32 v85, vcc, 0, v5, vcc
	v_add_co_u32_e32 v86, vcc, 0x120000, v4
	s_lshl_b32 s4, s1, 6
	s_nop 0
	v_addc_co_u32_e32 v87, vcc, 0, v5, vcc
	v_add_co_u32_e32 v88, vcc, 0x168000, v4
	s_mul_i32 s1, s1, 0xffff7000
	s_nop 0
	v_addc_co_u32_e32 v89, vcc, 0, v5, vcc
	v_add_co_u32_e32 v90, vcc, 0x1b0000, v4
	s_ashr_i32 s5, s4, 31
	s_nop 0
	v_addc_co_u32_e32 v91, vcc, 0, v5, vcc
	v_add_co_u32_e32 v92, vcc, 0x1f8000, v4
	s_add_i32 s10, s20, s13
	s_nop 0
	v_addc_co_u32_e32 v93, vcc, 0, v5, vcc
	global_load_dword v79, v[4:5], off nt
	s_nop 0
	global_load_dword v80, v[80:81], off nt
	s_nop 0
	global_load_dword v81, v[82:83], off nt
	s_nop 0
	global_load_dword v82, v[84:85], off nt
	global_load_dword v83, v[86:87], off nt
	s_nop 0
	global_load_dword v84, v[88:89], off nt
	global_load_dword v85, v[90:91], off nt
	global_load_dword v86, v[92:93], off nt
	v_add_co_u32_e32 v88, vcc, 0x240000, v4
	v_readlane_b32 s77, v254, 3
	s_nop 0
	v_addc_co_u32_e32 v89, vcc, 0, v5, vcc
	v_add_co_u32_e32 v90, vcc, 0x288000, v4
	v_readlane_b32 s78, v254, 4
	s_nop 0
	v_addc_co_u32_e32 v91, vcc, 0, v5, vcc
	v_add_co_u32_e32 v92, vcc, 0x2d0000, v4
	v_readlane_b32 s79, v254, 5
	s_nop 0
	v_addc_co_u32_e32 v93, vcc, 0, v5, vcc
	v_add_co_u32_e32 v94, vcc, 0x318000, v4
	v_readlane_b32 s80, v254, 6
	s_nop 0
	v_addc_co_u32_e32 v95, vcc, 0, v5, vcc
	v_add_co_u32_e32 v96, vcc, 0x360000, v4
	v_readlane_b32 s81, v254, 7
	s_nop 0
	v_addc_co_u32_e32 v97, vcc, 0, v5, vcc
	v_add_co_u32_e32 v98, vcc, 0x3a8000, v4
	v_readlane_b32 s82, v254, 8
	s_nop 0
	v_addc_co_u32_e32 v99, vcc, 0, v5, vcc
	v_add_co_u32_e32 v100, vcc, 0x3f0000, v4
	v_readlane_b32 s83, v254, 9
	s_nop 0
	v_addc_co_u32_e32 v101, vcc, 0, v5, vcc
	v_add_co_u32_e32 v102, vcc, 0x438000, v4
	v_readlane_b32 s86, v254, 12
	s_nop 0
	v_addc_co_u32_e32 v103, vcc, 0, v5, vcc
	global_load_dword v87, v[88:89], off nt
	s_nop 0
	global_load_dword v88, v[90:91], off nt
	global_load_dword v89, v[92:93], off nt
	s_nop 0
	global_load_dword v90, v[94:95], off nt
	global_load_dword v91, v[96:97], off nt
	global_load_dword v92, v[98:99], off nt
	global_load_dword v93, v[100:101], off nt
	s_nop 0
	global_load_dword v94, v[102:103], off nt
	v_add_co_u32_e32 v96, vcc, 0x480000, v4
	v_readlane_b32 s87, v254, 13
	s_nop 0
	v_addc_co_u32_e32 v97, vcc, 0, v5, vcc
	v_add_co_u32_e32 v98, vcc, 0x4c8000, v4
	v_readlane_b32 s88, v254, 14
	s_nop 0
	v_addc_co_u32_e32 v99, vcc, 0, v5, vcc
	v_add_co_u32_e32 v100, vcc, 0x510000, v4
	v_readlane_b32 s89, v254, 15
	s_nop 0
	v_addc_co_u32_e32 v101, vcc, 0, v5, vcc
	v_add_co_u32_e32 v102, vcc, 0x558000, v4
	v_readlane_b32 s90, v254, 16
	s_nop 0
	v_addc_co_u32_e32 v103, vcc, 0, v5, vcc
	v_add_co_u32_e32 v104, vcc, 0x5a0000, v4
	v_readlane_b32 s91, v254, 17
	s_nop 0
	v_addc_co_u32_e32 v105, vcc, 0, v5, vcc
	v_add_co_u32_e32 v106, vcc, 0x5e8000, v4
	s_nop 1
	v_addc_co_u32_e32 v107, vcc, 0, v5, vcc
	v_add_co_u32_e32 v108, vcc, 0x630000, v4
	s_nop 1
	v_addc_co_u32_e32 v109, vcc, 0, v5, vcc
	v_add_co_u32_e32 v110, vcc, 0x678000, v4
	s_nop 1
	v_addc_co_u32_e32 v111, vcc, 0, v5, vcc
	global_load_dword v95, v[96:97], off nt
	s_nop 0
	global_load_dword v96, v[98:99], off nt
	global_load_dword v97, v[100:101], off nt
	s_nop 0
	global_load_dword v98, v[102:103], off nt
	global_load_dword v99, v[104:105], off nt
	global_load_dword v100, v[106:107], off nt
	global_load_dword v101, v[108:109], off nt
	s_nop 0
	global_load_dword v102, v[110:111], off nt
	v_add_co_u32_e32 v104, vcc, 0x6c0000, v4
	s_nop 1
	v_addc_co_u32_e32 v105, vcc, 0, v5, vcc
	v_add_co_u32_e32 v106, vcc, 0x708000, v4
	s_nop 1
	v_addc_co_u32_e32 v107, vcc, 0, v5, vcc
	v_add_co_u32_e32 v108, vcc, 0x750000, v4
	s_nop 1
	v_addc_co_u32_e32 v109, vcc, 0, v5, vcc
	v_add_co_u32_e32 v110, vcc, 0x798000, v4
	s_nop 1
	v_addc_co_u32_e32 v111, vcc, 0, v5, vcc
	v_add_co_u32_e32 v112, vcc, 0x7e0000, v4
	s_nop 1
	v_addc_co_u32_e32 v113, vcc, 0, v5, vcc
	v_add_co_u32_e32 v114, vcc, 0x828000, v4
	s_nop 1
	v_addc_co_u32_e32 v115, vcc, 0, v5, vcc
	v_add_co_u32_e32 v116, vcc, 0x870000, v4
	s_nop 1
	v_addc_co_u32_e32 v117, vcc, 0, v5, vcc
	v_add_co_u32_e32 v4, vcc, 0x8b8000, v4
	s_nop 1
	v_addc_co_u32_e32 v5, vcc, 0, v5, vcc
	global_load_dword v103, v[104:105], off nt
	s_nop 0
	global_load_dword v104, v[106:107], off nt
	global_load_dword v105, v[108:109], off nt
	s_nop 0
	global_load_dword v106, v[110:111], off nt
	global_load_dword v107, v[112:113], off nt
	global_load_dword v108, v[114:115], off nt
	global_load_dword v109, v[116:117], off nt
	s_nop 0
	global_load_dword v110, v[4:5], off nt
	v_add_u32_e32 v111, 0x400, v65
	v_add_u32_e32 v112, 0x800, v65
	v_add_u32_e32 v113, 0xc00, v65
	v_add_u32_e32 v114, 0x1000, v65
	v_add_u32_e32 v115, 0x1400, v65
	v_add_u32_e32 v116, 0x1800, v65
	v_add_u32_e32 v117, 0x1c00, v65
	s_waitcnt vmcnt(63)
; #define GAS __attribute__((address_space(1)))
; #define LAS __attribute__((address_space(3)))
; #define LDS_WAIT() asm volatile("s_waitcnt lgkmcnt(0)" ::: "memory")
; __device__ __forceinline__ unsigned pk2(float lo, float hi) { return pg8::cvt_pk_bf16(lo, hi); }
; __device__ __forceinline__ int src_col(int mat, int c) {
;     ...
;     if (mat == 2) {
;         if (c < CW) return CW + c;
;         const int cc = c - CW, tile = cc >> 8, w = cc & 255;
;         return w < 128 ? (tile * 128 + w) : (2 * CW + tile * 128 + (w - 128));
;     }
;     return c;
; }
; __device__ __forceinline__ void tr_load(const float* W, int N, int mat, int item, int lane, int nblk, float (&x)[32]) {
;     const int kb = item / nblk, nb = item % nblk, k0 = 64 * kb, n0 = 32 * nb;
;     const int sc = src_col(mat, n0 + (lane & 31));
; #pragma unroll
;     for (int i = 0; i < 32; ++i) { const int kk = 2 * i + (lane >> 5); x[i] = sc >= 0 ? W[(size_t)(k0 + kk) * N + sc] : 0.f; }
; }
; __device__ __forceinline__ void tr_load_nc(const float* W, int N, int mat, int item, int lane, int nblk, float (&x)[32]) {
;     const int kb = item / nblk, nb = item % nblk, k0 = 64 * kb, n0 = 32 * nb;
;     const int sc = src_col(mat, n0 + (lane & 31));
;     const float* wp = W + (size_t)(k0 + (lane >> 5)) * N + sc;
; #pragma unroll
;     for (int i = 0; i < 32; ++i) x[i] = wp[(size_t)(2 * i) * N];
; }
; __device__ __forceinline__ void tr_store(bf16* WT, int K, LAS float* scr, int item, int lane, int nblk, const float (&x)[32]) {
;     const int kb = item / nblk, nb = item % nblk, k0 = 64 * kb, n0 = 32 * nb;
; #pragma unroll
;     for (int i = 0; i < 32; ++i) { const int kk = 2 * i + (lane >> 5); scr[kk * 33 + (lane & 31)] = x[i]; }
;     LDS_WAIT(); asm volatile("" ::: "memory");
;     const int c = lane & 7;
; #pragma unroll
;     for (int j = 0; j < 4; ++j) { const int n = (lane >> 3) + 8 * j; const LAS float* s = scr + (8 * c) * 33 + n;
;         v4u o; o.x = pk2(s[0 * 33], s[1 * 33]); o.y = pk2(s[2 * 33], s[3 * 33]); o.z = pk2(s[4 * 33], s[5 * 33]); o.w = pk2(s[6 * 33], s[7 * 33]);
;         *(GAS v4u*)(WT + (size_t)(n0 + n) * K + k0 + 8 * c) = o; }
;     LDS_WAIT(); asm volatile("" ::: "memory");
; }
	ds_write2_b32 v65, v8, v11 offset1:66
	ds_write2_b32 v65, v10, v14 offset0:132 offset1:198
	ds_write2_b32 v111, v9, v13 offset0:8 offset1:74
	ds_write2_b32 v111, v12, v15 offset0:140 offset1:206
	ds_write2_b32 v112, v16, v19 offset0:16 offset1:82
	ds_write2_b32 v112, v18, v22 offset0:148 offset1:214
	ds_write2_b32 v113, v17, v21 offset0:24 offset1:90
	ds_write2_b32 v113, v20, v23 offset0:156 offset1:222
	ds_write2_b32 v114, v32, v35 offset0:32 offset1:98
	ds_write2_b32 v114, v34, v38 offset0:164 offset1:230
	ds_write2_b32 v115, v33, v37 offset0:40 offset1:106
	ds_write2_b32 v115, v36, v39 offset0:172 offset1:238
	ds_write2_b32 v116, v48, v51 offset0:48 offset1:114
	ds_write2_b32 v116, v50, v54 offset0:180 offset1:246
	ds_write2_b32 v117, v49, v53 offset0:56 offset1:122
	ds_write2_b32 v117, v52, v55 offset0:188 offset1:254
	s_waitcnt lgkmcnt(0)
	ds_read2_b32 v[4:5], v74 offset1:33
	s_waitcnt lgkmcnt(0)
	v_cvt_pk_bf16_f32 v8, v4, v5
	ds_read2_b32 v[4:5], v74 offset0:66 offset1:99
	s_waitcnt lgkmcnt(0)
	v_cvt_pk_bf16_f32 v9, v4, v5
	ds_read2_b32 v[4:5], v74 offset0:132 offset1:165
	s_waitcnt lgkmcnt(0)
	v_cvt_pk_bf16_f32 v10, v4, v5
	ds_read2_b32 v[4:5], v74 offset0:198 offset1:231
	s_waitcnt lgkmcnt(0)
	v_cvt_pk_bf16_f32 v11, v4, v5
	v_add_u32_e32 v4, s1, v78
	v_ashrrev_i32_e32 v5, 31, v4
	v_lshl_add_u64 v[12:13], s[4:5], 1, v[2:3]
	v_lshlrev_b64 v[16:17], 13, v[4:5]
	v_lshl_add_u64 v[16:17], v[12:13], 0, v[16:17]
	ds_read2_b32 v[14:15], v74 offset0:8 offset1:41
	global_store_dwordx4 v[16:17], v[8:11], off
	s_min_i32 s4, s10, 0x6fff
	s_mul_hi_i32 s1, s4, 0x38e38e39
	s_waitcnt lgkmcnt(0)
	v_cvt_pk_bf16_f32 v8, v14, v15
	ds_read2_b32 v[10:11], v74 offset0:74 offset1:107
	s_waitcnt lgkmcnt(0)
	v_cvt_pk_bf16_f32 v9, v10, v11
	ds_read2_b32 v[10:11], v74 offset0:140 offset1:173
	s_waitcnt lgkmcnt(0)
	v_cvt_pk_bf16_f32 v10, v10, v11
	ds_read2_b32 v[14:15], v74 offset0:206 offset1:239
	s_waitcnt lgkmcnt(0)
	v_cvt_pk_bf16_f32 v11, v14, v15
	v_add_u32_e32 v14, 8, v4
	v_ashrrev_i32_e32 v15, 31, v14
	v_lshlrev_b64 v[14:15], 13, v[14:15]
	v_lshl_add_u64 v[14:15], v[12:13], 0, v[14:15]
	ds_read2_b32 v[16:17], v74 offset0:16 offset1:49
	global_store_dwordx4 v[14:15], v[8:11], off
	s_lshr_b32 s5, s1, 31
	s_ashr_i32 s1, s1, 8
	s_waitcnt lgkmcnt(0)
	v_cvt_pk_bf16_f32 v8, v16, v17
	ds_read2_b32 v[10:11], v74 offset0:82 offset1:115
	s_waitcnt lgkmcnt(0)
	v_cvt_pk_bf16_f32 v9, v10, v11
	ds_read2_b32 v[10:11], v74 offset0:148 offset1:181
	s_waitcnt lgkmcnt(0)
	v_cvt_pk_bf16_f32 v10, v10, v11
	ds_read2_b32 v[14:15], v74 offset0:214 offset1:247
	s_waitcnt lgkmcnt(0)
	v_cvt_pk_bf16_f32 v11, v14, v15
	v_add_u32_e32 v14, 16, v4
	v_ashrrev_i32_e32 v15, 31, v14
	v_lshlrev_b64 v[14:15], 13, v[14:15]
	v_add_u32_e32 v4, 24, v4
	v_lshl_add_u64 v[14:15], v[12:13], 0, v[14:15]
	v_ashrrev_i32_e32 v5, 31, v4
	ds_read2_b32 v[16:17], v74 offset0:24 offset1:57
	global_store_dwordx4 v[14:15], v[8:11], off
	v_lshlrev_b64 v[4:5], 13, v[4:5]
	v_lshl_add_u64 v[4:5], v[12:13], 0, v[4:5]
	s_waitcnt lgkmcnt(0)
	v_cvt_pk_bf16_f32 v8, v16, v17
	ds_read2_b32 v[10:11], v74 offset0:90 offset1:123
	s_waitcnt lgkmcnt(0)
	v_cvt_pk_bf16_f32 v9, v10, v11
	ds_read2_b32 v[10:11], v74 offset0:156 offset1:189
	s_add_i32 s1, s1, s5
	s_waitcnt lgkmcnt(0)
	v_cvt_pk_bf16_f32 v10, v10, v11
	ds_read2_b32 v[14:15], v74 offset0:222 offset1:255
	s_waitcnt lgkmcnt(0)
	v_cvt_pk_bf16_f32 v11, v14, v15
	global_store_dwordx4 v[4:5], v[8:11], off
	s_mul_i32 s5, s1, 0x480
	s_waitcnt lgkmcnt(0)
	s_sub_i32 s4, s4, s5
	s_lshl_b32 s6, s4, 5
	v_or_b32_e32 v5, s6, v6
	v_cmp_lt_i32_e32 vcc, s17, v5
	s_and_saveexec_b64 s[4:5], vcc
	s_xor_b64 s[4:5], exec, s[4:5]
	s_cbranch_execz .LBB0_697
	s_add_i32 s21, s6, 0xffffd000
	s_lshr_b32 s21, s21, 1
	v_cmp_gt_u32_sdwa s[6:7], v5, s18 src0_sel:BYTE_0 src1_sel:DWORD
	s_and_b32 s21, s21, 0x7fffff80
	s_and_saveexec_b64 s[22:23], s[6:7]
	s_xor_b64 s[6:7], exec, s[22:23]
	v_add_u32_sdwa v4, v5, s21 dst_sel:DWORD dst_unused:UNUSED_PAD src0_sel:BYTE_0 src1_sel:DWORD
	v_add_u32_e32 v4, 0x5f80, v4
	s_andn2_saveexec_b64 s[6:7], s[6:7]
	v_or_b32_sdwa v4, s21, v5 dst_sel:DWORD dst_unused:UNUSED_PAD src0_sel:DWORD src1_sel:BYTE_0
	s_or_b64 exec, exec, s[6:7]
.LBB0_697:
	s_andn2_saveexec_b64 s[4:5], s[4:5]
	v_add_u32_e32 v4, 0x3000, v5
	s_or_b64 exec, exec, s[4:5]
	v_readlane_b32 s76, v254, 2
	v_readlane_b32 s84, v254, 10
	v_readlane_b32 s85, v254, 11
	v_lshl_or_b32 v5, s1, 6, v7
	s_add_i32 s1, s15, s20
	v_mov_b64_e32 v[8:9], s[84:85]
	v_mad_i64_i32 v[8:9], s[4:5], v5, s11, v[8:9]
	v_ashrrev_i32_e32 v5, 31, v4
	v_lshl_add_u64 v[4:5], v[4:5], 2, v[8:9]
	v_add_co_u32_e32 v10, vcc, 0x48000, v4
	s_mul_hi_i32 s4, s1, 0x38e38e39
	s_nop 0
	v_addc_co_u32_e32 v11, vcc, 0, v5, vcc
	v_add_co_u32_e32 v12, vcc, 0x90000, v4
	s_lshr_b32 s5, s4, 31
	s_nop 0
	v_addc_co_u32_e32 v13, vcc, 0, v5, vcc
	v_add_co_u32_e32 v14, vcc, 0xd8000, v4
	s_ashr_i32 s4, s4, 8
	s_nop 0
	v_addc_co_u32_e32 v15, vcc, 0, v5, vcc
	v_add_co_u32_e32 v16, vcc, 0x120000, v4
	s_add_i32 s5, s4, s5
	s_nop 0
	v_addc_co_u32_e32 v17, vcc, 0, v5, vcc
	v_add_co_u32_e32 v18, vcc, 0x168000, v4
	s_lshl_b32 s4, s5, 6
	s_nop 0
	v_addc_co_u32_e32 v19, vcc, 0, v5, vcc
	v_add_co_u32_e32 v20, vcc, 0x1b0000, v4
	s_mulk_i32 s5, 0x480
	s_nop 0
	v_addc_co_u32_e32 v21, vcc, 0, v5, vcc
	v_add_co_u32_e32 v22, vcc, 0x1f8000, v4
	s_sub_i32 s1, s1, s5
	s_nop 0
	v_addc_co_u32_e32 v23, vcc, 0, v5, vcc
	global_load_dword v8, v[4:5], off nt
	s_nop 0
	global_load_dword v11, v[10:11], off nt
	s_nop 0
	global_load_dword v10, v[12:13], off nt
	s_nop 0
	global_load_dword v14, v[14:15], off nt
	s_nop 0
	global_load_dword v9, v[16:17], off nt
	global_load_dword v13, v[18:19], off nt
; __device__ __forceinline__ void tr_load_nc(const float* W, int N, int mat, int item, int lane, int nblk, float (&x)[32]) {
;     const int kb = item / nblk, nb = item % nblk, k0 = 64 * kb, n0 = 32 * nb;
;     const int sc = src_col(mat, n0 + (lane & 31));
;     const float* wp = W + (size_t)(k0 + (lane >> 5)) * N + sc;
; #pragma unroll
;     for (int i = 0; i < 32; ++i) x[i] = wp[(size_t)(2 * i) * N];
; }
	global_load_dword v12, v[20:21], off nt
	global_load_dword v15, v[22:23], off nt
	v_add_co_u32_e32 v16, vcc, 0x240000, v4
	s_lshl_b32 s1, s1, 5
	s_nop 0
	v_addc_co_u32_e32 v17, vcc, 0, v5, vcc
	v_add_co_u32_e32 v18, vcc, 0x288000, v4
	s_ashr_i32 s5, s4, 31
	s_nop 0
	v_addc_co_u32_e32 v19, vcc, 0, v5, vcc
	v_add_co_u32_e32 v20, vcc, 0x2d0000, v4
	v_readlane_b32 s77, v254, 3
	s_nop 0
	v_addc_co_u32_e32 v21, vcc, 0, v5, vcc
	v_add_co_u32_e32 v22, vcc, 0x318000, v4
	v_readlane_b32 s78, v254, 4
	s_nop 0
	v_addc_co_u32_e32 v23, vcc, 0, v5, vcc
	v_add_co_u32_e32 v32, vcc, 0x360000, v4
	v_readlane_b32 s79, v254, 5
	s_nop 0
	v_addc_co_u32_e32 v33, vcc, 0, v5, vcc
	v_add_co_u32_e32 v34, vcc, 0x3a8000, v4
	v_readlane_b32 s80, v254, 6
	s_nop 0
	v_addc_co_u32_e32 v35, vcc, 0, v5, vcc
	v_add_co_u32_e32 v36, vcc, 0x3f0000, v4
	v_readlane_b32 s81, v254, 7
	s_nop 0
	v_addc_co_u32_e32 v37, vcc, 0, v5, vcc
	v_add_co_u32_e32 v38, vcc, 0x438000, v4
	v_readlane_b32 s82, v254, 8
	s_nop 0
	v_addc_co_u32_e32 v39, vcc, 0, v5, vcc
	global_load_dword v16, v[16:17], off nt
	s_nop 0
	global_load_dword v19, v[18:19], off nt
	s_nop 0
	global_load_dword v18, v[20:21], off nt
	s_nop 0
	global_load_dword v22, v[22:23], off nt
	s_nop 0
	global_load_dword v17, v[32:33], off nt
	global_load_dword v21, v[34:35], off nt
	global_load_dword v20, v[36:37], off nt
	global_load_dword v23, v[38:39], off nt
	v_add_co_u32_e32 v32, vcc, 0x480000, v4
	v_readlane_b32 s83, v254, 9
	s_nop 0
	v_addc_co_u32_e32 v33, vcc, 0, v5, vcc
	v_add_co_u32_e32 v34, vcc, 0x4c8000, v4
	v_readlane_b32 s86, v254, 12
	s_nop 0
	v_addc_co_u32_e32 v35, vcc, 0, v5, vcc
	v_add_co_u32_e32 v36, vcc, 0x510000, v4
	v_readlane_b32 s87, v254, 13
	s_nop 0
	v_addc_co_u32_e32 v37, vcc, 0, v5, vcc
	v_add_co_u32_e32 v38, vcc, 0x558000, v4
	v_readlane_b32 s88, v254, 14
	s_nop 0
	v_addc_co_u32_e32 v39, vcc, 0, v5, vcc
	v_add_co_u32_e32 v48, vcc, 0x5a0000, v4
	v_readlane_b32 s89, v254, 15
	s_nop 0
	v_addc_co_u32_e32 v49, vcc, 0, v5, vcc
	v_add_co_u32_e32 v50, vcc, 0x5e8000, v4
	v_readlane_b32 s90, v254, 16
	s_nop 0
	v_addc_co_u32_e32 v51, vcc, 0, v5, vcc
	v_add_co_u32_e32 v52, vcc, 0x630000, v4
	v_readlane_b32 s91, v254, 17
	s_nop 0
	v_addc_co_u32_e32 v53, vcc, 0, v5, vcc
	v_add_co_u32_e32 v54, vcc, 0x678000, v4
	s_nop 1
	v_addc_co_u32_e32 v55, vcc, 0, v5, vcc
	global_load_dword v32, v[32:33], off nt
	s_nop 0
	global_load_dword v35, v[34:35], off nt
	s_nop 0
	global_load_dword v34, v[36:37], off nt
	s_nop 0
	global_load_dword v38, v[38:39], off nt
	s_nop 0
	global_load_dword v33, v[48:49], off nt
	global_load_dword v37, v[50:51], off nt
	global_load_dword v36, v[52:53], off nt
	global_load_dword v39, v[54:55], off nt
	v_add_co_u32_e32 v48, vcc, 0x6c0000, v4
	s_nop 1
	v_addc_co_u32_e32 v49, vcc, 0, v5, vcc
	v_add_co_u32_e32 v50, vcc, 0x708000, v4
	s_nop 1
	v_addc_co_u32_e32 v51, vcc, 0, v5, vcc
	v_add_co_u32_e32 v52, vcc, 0x750000, v4
	s_nop 1
	v_addc_co_u32_e32 v53, vcc, 0, v5, vcc
	v_add_co_u32_e32 v54, vcc, 0x798000, v4
	s_nop 1
	v_addc_co_u32_e32 v55, vcc, 0, v5, vcc
	v_add_co_u32_e32 v118, vcc, 0x7e0000, v4
	s_nop 1
	v_addc_co_u32_e32 v119, vcc, 0, v5, vcc
	v_add_co_u32_e32 v120, vcc, 0x828000, v4
	s_nop 1
	v_addc_co_u32_e32 v121, vcc, 0, v5, vcc
	v_add_co_u32_e32 v122, vcc, 0x870000, v4
	s_nop 1
	v_addc_co_u32_e32 v123, vcc, 0, v5, vcc
	v_add_co_u32_e32 v4, vcc, 0x8b8000, v4
	s_nop 1
	v_addc_co_u32_e32 v5, vcc, 0, v5, vcc
	global_load_dword v48, v[48:49], off nt
	s_nop 0
	global_load_dword v51, v[50:51], off nt
	s_nop 0
	global_load_dword v50, v[52:53], off nt
	s_nop 0
	global_load_dword v54, v[54:55], off nt
	s_nop 0
	global_load_dword v49, v[118:119], off nt
	global_load_dword v53, v[120:121], off nt
	global_load_dword v52, v[122:123], off nt
	global_load_dword v55, v[4:5], off nt
	s_waitcnt vmcnt(63)
; #define GAS __attribute__((address_space(1)))
; #define LAS __attribute__((address_space(3)))
; #define LDS_WAIT() asm volatile("s_waitcnt lgkmcnt(0)" ::: "memory")
; __device__ __forceinline__ unsigned pk2(float lo, float hi) { return pg8::cvt_pk_bf16(lo, hi); }
; __device__ __forceinline__ int src_col(int mat, int c) {
;     ...
;     if (mat == 2) {
;         if (c < CW) return CW + c;
;         const int cc = c - CW, tile = cc >> 8, w = cc & 255;
;         return w < 128 ? (tile * 128 + w) : (2 * CW + tile * 128 + (w - 128));
;     }
;     return c;
; }
; __device__ __forceinline__ void tr_load(const float* W, int N, int mat, int item, int lane, int nblk, float (&x)[32]) {
;     const int kb = item / nblk, nb = item % nblk, k0 = 64 * kb, n0 = 32 * nb;
;     const int sc = src_col(mat, n0 + (lane & 31));
; #pragma unroll
;     for (int i = 0; i < 32; ++i) { const int kk = 2 * i + (lane >> 5); x[i] = sc >= 0 ? W[(size_t)(k0 + kk) * N + sc] : 0.f; }
; }
; __device__ __forceinline__ void tr_load_nc(const float* W, int N, int mat, int item, int lane, int nblk, float (&x)[32]) {
;     const int kb = item / nblk, nb = item % nblk, k0 = 64 * kb, n0 = 32 * nb;
;     const int sc = src_col(mat, n0 + (lane & 31));
;     const float* wp = W + (size_t)(k0 + (lane >> 5)) * N + sc;
; #pragma unroll
;     for (int i = 0; i < 32; ++i) x[i] = wp[(size_t)(2 * i) * N];
; }
; __device__ __forceinline__ void tr_store(bf16* WT, int K, LAS float* scr, int item, int lane, int nblk, const float (&x)[32]) {
;     const int kb = item / nblk, nb = item % nblk, k0 = 64 * kb, n0 = 32 * nb;
; #pragma unroll
;     for (int i = 0; i < 32; ++i) { const int kk = 2 * i + (lane >> 5); scr[kk * 33 + (lane & 31)] = x[i]; }
;     LDS_WAIT(); asm volatile("" ::: "memory");
;     const int c = lane & 7;
; #pragma unroll
;     for (int j = 0; j < 4; ++j) { const int n = (lane >> 3) + 8 * j; const LAS float* s = scr + (8 * c) * 33 + n;
;         v4u o; o.x = pk2(s[0 * 33], s[1 * 33]); o.y = pk2(s[2 * 33], s[3 * 33]); o.z = pk2(s[4 * 33], s[5 * 33]); o.w = pk2(s[6 * 33], s[7 * 33]);
;         *(GAS v4u*)(WT + (size_t)(n0 + n) * K + k0 + 8 * c) = o; }
;     LDS_WAIT(); asm volatile("" ::: "memory");
; }
	ds_write2_b32 v65, v24, v26 offset1:66
	ds_write2_b32 v65, v25, v28 offset0:132 offset1:198
	ds_write2_b32 v111, v27, v30 offset0:8 offset1:74
	ds_write2_b32 v111, v29, v31 offset0:140 offset1:206
	ds_write2_b32 v112, v40, v42 offset0:16 offset1:82
	ds_write2_b32 v112, v41, v44 offset0:148 offset1:214
	ds_write2_b32 v113, v43, v46 offset0:24 offset1:90
	ds_write2_b32 v113, v45, v47 offset0:156 offset1:222
	ds_write2_b32 v114, v56, v58 offset0:32 offset1:98
	ds_write2_b32 v114, v57, v60 offset0:164 offset1:230
	ds_write2_b32 v115, v59, v62 offset0:40 offset1:106
	ds_write2_b32 v115, v61, v63 offset0:172 offset1:238
	ds_write2_b32 v116, v64, v67 offset0:48 offset1:114
	ds_write2_b32 v116, v66, v70 offset0:180 offset1:246
	ds_write2_b32 v117, v69, v72 offset0:56 offset1:122
	ds_write2_b32 v117, v71, v73 offset0:188 offset1:254
	s_waitcnt lgkmcnt(0)
	ds_read2_b32 v[4:5], v74 offset1:33
	s_waitcnt lgkmcnt(0)
	v_cvt_pk_bf16_f32 v24, v4, v5
	ds_read2_b32 v[4:5], v74 offset0:66 offset1:99
	s_waitcnt lgkmcnt(0)
	v_cvt_pk_bf16_f32 v25, v4, v5
	ds_read2_b32 v[4:5], v74 offset0:132 offset1:165
	s_waitcnt lgkmcnt(0)
	v_cvt_pk_bf16_f32 v26, v4, v5
	ds_read2_b32 v[4:5], v74 offset0:198 offset1:231
	s_waitcnt lgkmcnt(0)
	v_cvt_pk_bf16_f32 v27, v4, v5
	v_or_b32_e32 v4, s1, v68
	v_ashrrev_i32_e32 v5, 31, v4
	v_lshl_add_u64 v[28:29], s[4:5], 1, v[2:3]
	v_lshlrev_b64 v[4:5], 13, v[4:5]
	v_lshl_add_u64 v[4:5], v[28:29], 0, v[4:5]
	ds_read2_b32 v[30:31], v74 offset0:8 offset1:41
	global_store_dwordx4 v[4:5], v[24:27], off
	s_waitcnt lgkmcnt(0)
	s_nop 0
	v_cvt_pk_bf16_f32 v24, v30, v31
	ds_read2_b32 v[4:5], v74 offset0:74 offset1:107
	s_waitcnt lgkmcnt(0)
	v_cvt_pk_bf16_f32 v25, v4, v5
	ds_read2_b32 v[4:5], v74 offset0:140 offset1:173
	s_waitcnt lgkmcnt(0)
	v_cvt_pk_bf16_f32 v26, v4, v5
	ds_read2_b32 v[4:5], v74 offset0:206 offset1:239
	s_waitcnt lgkmcnt(0)
	v_cvt_pk_bf16_f32 v27, v4, v5
	v_or_b32_e32 v4, s1, v75
	v_ashrrev_i32_e32 v5, 31, v4
	v_lshlrev_b64 v[4:5], 13, v[4:5]
	v_lshl_add_u64 v[4:5], v[28:29], 0, v[4:5]
	ds_read2_b32 v[30:31], v74 offset0:16 offset1:49
	global_store_dwordx4 v[4:5], v[24:27], off
	s_waitcnt lgkmcnt(0)
	s_nop 0
	v_cvt_pk_bf16_f32 v24, v30, v31
	ds_read2_b32 v[4:5], v74 offset0:82 offset1:115
	s_waitcnt lgkmcnt(0)
	v_cvt_pk_bf16_f32 v25, v4, v5
	ds_read2_b32 v[4:5], v74 offset0:148 offset1:181
	s_waitcnt lgkmcnt(0)
	v_cvt_pk_bf16_f32 v26, v4, v5
	ds_read2_b32 v[4:5], v74 offset0:214 offset1:247
	s_waitcnt lgkmcnt(0)
	v_cvt_pk_bf16_f32 v27, v4, v5
	v_or_b32_e32 v4, s1, v76
	v_ashrrev_i32_e32 v5, 31, v4
	v_lshlrev_b64 v[4:5], 13, v[4:5]
	v_lshl_add_u64 v[4:5], v[28:29], 0, v[4:5]
	ds_read2_b32 v[30:31], v74 offset0:24 offset1:57
	global_store_dwordx4 v[4:5], v[24:27], off
	s_waitcnt lgkmcnt(0)
	s_nop 0
	v_cvt_pk_bf16_f32 v24, v30, v31
	ds_read2_b32 v[4:5], v74 offset0:90 offset1:123
	s_waitcnt lgkmcnt(0)
	v_cvt_pk_bf16_f32 v25, v4, v5
	ds_read2_b32 v[4:5], v74 offset0:156 offset1:189
	s_waitcnt lgkmcnt(0)
	v_cvt_pk_bf16_f32 v26, v4, v5
	ds_read2_b32 v[4:5], v74 offset0:222 offset1:255
	s_waitcnt lgkmcnt(0)
	v_cvt_pk_bf16_f32 v27, v4, v5
	v_or_b32_e32 v4, s1, v77
	s_add_i32 s1, s16, s20
	s_min_i32 s4, s1, 0x6fff
	v_ashrrev_i32_e32 v5, 31, v4
	s_mul_hi_i32 s1, s4, 0x38e38e39
	v_lshlrev_b64 v[4:5], 13, v[4:5]
	s_lshr_b32 s5, s1, 31
	s_ashr_i32 s1, s1, 8
	v_lshl_add_u64 v[4:5], v[28:29], 0, v[4:5]
	s_add_i32 s1, s1, s5
	global_store_dwordx4 v[4:5], v[24:27], off
	s_mul_i32 s5, s1, 0x480
	s_waitcnt lgkmcnt(0)
	s_sub_i32 s4, s4, s5
	s_lshl_b32 s6, s4, 5
	v_or_b32_e32 v5, s6, v6
	v_cmp_lt_i32_e32 vcc, s17, v5
	s_and_saveexec_b64 s[4:5], vcc
	s_xor_b64 s[4:5], exec, s[4:5]
	s_cbranch_execz .LBB0_705
	s_add_i32 s20, s6, 0xffffd000
	s_lshr_b32 s20, s20, 1
	v_cmp_gt_u32_sdwa s[6:7], v5, s18 src0_sel:BYTE_0 src1_sel:DWORD
	s_and_b32 s20, s20, 0x7fffff80
	s_and_saveexec_b64 s[22:23], s[6:7]
	s_xor_b64 s[6:7], exec, s[22:23]
	v_add_u32_sdwa v4, v5, s20 dst_sel:DWORD dst_unused:UNUSED_PAD src0_sel:BYTE_0 src1_sel:DWORD
	v_add_u32_e32 v4, 0x5f80, v4
	s_andn2_saveexec_b64 s[6:7], s[6:7]
	v_or_b32_sdwa v4, s20, v5 dst_sel:DWORD dst_unused:UNUSED_PAD src0_sel:DWORD src1_sel:BYTE_0
	s_or_b64 exec, exec, s[6:7]

; #define GAS __attribute__((address_space(1)))
; __device__ __forceinline__ void norm_phase(const Args& a, LAS unsigned char* lds, int layer, const float* xlat, const float* xctx, int nrows, const bf16* yadd, bf16* xout) {
;     ...
;     __syncthreads();
;     bf16* H = (bf16*)(a.ws + WS_H);
;     const int gw = blockIdx.x * NWAVES + wave, NGW = gridDim.x * NWAVES;
;     f32x4 v[16], vn[16]; v2u yv[16], yn[16];
;     auto loadrow = [&](int row, f32x4 (&dst)[16], v2u (&yd)[16]) {
;         const float* xr = (row < MLAT) ? xlat + (size_t)row * D : xctx + (size_t)(row - MLAT) * D;
;         const GAS f32x4* xp = (const GAS f32x4*)xr + lane;
; #pragma unroll
;         for (int q = 0; q < 16; ++q) dst[q] = xp[64 * q];
;         if (yadd) { const GAS v2u* yp = (const GAS v2u*)(yadd + (size_t)row * D) + lane;
; #pragma unroll
;             for (int q = 0; q < 16; ++q) yd[q] = yp[64 * q]; }
;     };
;     int row = gw;
;     if (row < nrows) loadrow(row, v, yv);
.LBB0_921:
	s_or_b64 exec, exec, s[0:1]
	s_ashr_i32 s0, s16, 6
	s_add_i32 s12, s0, s33
	s_cmpk_lt_i32 s12, 0x4000
	s_waitcnt vmcnt(0) lgkmcnt(0)
	s_barrier
	s_cbranch_scc0 .LBB0_926
	s_ashr_i32 s13, s12, 31
	s_lshl_b64 s[0:1], s[12:13], 14
	v_and_b32_e32 v1, 63, v2
	s_add_u32 s0, s52, s0
	s_addc_u32 s1, s53, s1
	v_lshlrev_b32_e32 v2, 4, v1
	v_mov_b32_e32 v3, 0
	v_lshl_add_u64 v[4:5], s[0:1], 0, v[2:3]
	v_add_co_u32_e32 v6, vcc, 0x1000, v4
	global_load_dwordx4 v[126:129], v2, s[0:1] nt
	global_load_dwordx4 v[122:125], v2, s[0:1] offset:1024 nt
	global_load_dwordx4 v[118:121], v2, s[0:1] offset:2048 nt
	global_load_dwordx4 v[114:117], v2, s[0:1] offset:3072 nt
	v_addc_co_u32_e32 v7, vcc, 0, v5, vcc
	global_load_dwordx4 v[110:113], v[6:7], off nt
	global_load_dwordx4 v[106:109], v[6:7], off offset:1024 nt
	global_load_dwordx4 v[102:105], v[6:7], off offset:2048 nt
	global_load_dwordx4 v[98:101], v[6:7], off offset:3072 nt
	v_add_co_u32_e32 v6, vcc, 0x2000, v4
	s_lshl_b64 s[0:1], s[12:13], 13
	s_nop 0
	v_addc_co_u32_e32 v7, vcc, 0, v5, vcc
	v_add_co_u32_e32 v4, vcc, 0x3000, v4
	s_add_u32 s6, s50, s0
	s_nop 0
	v_addc_co_u32_e32 v5, vcc, 0, v5, vcc
	global_load_dwordx4 v[94:97], v[6:7], off nt
	global_load_dwordx4 v[90:93], v[6:7], off offset:1024 nt
	global_load_dwordx4 v[86:89], v[6:7], off offset:2048 nt
	global_load_dwordx4 v[82:85], v[6:7], off offset:3072 nt
	global_load_dwordx4 v[78:81], v[4:5], off nt
	global_load_dwordx4 v[74:77], v[4:5], off offset:1024 nt
	global_load_dwordx4 v[70:73], v[4:5], off offset:2048 nt
	global_load_dwordx4 v[66:69], v[4:5], off offset:3072 nt
	s_addc_u32 s7, s51, s1
	v_lshlrev_b32_e32 v4, 3, v1
	v_mov_b32_e32 v5, v3
	s_movk_i32 s14, 0x1000
	v_lshl_add_u64 v[6:7], s[6:7], 0, v[4:5]
	v_add_co_u32_e32 v6, vcc, s14, v6
	global_load_dwordx2 v[180:181], v4, s[6:7] nt
	global_load_dwordx2 v[200:201], v4, s[6:7] offset:512 nt
	global_load_dwordx2 v[198:199], v4, s[6:7] offset:1024 nt
	global_load_dwordx2 v[196:197], v4, s[6:7] offset:1536 nt
	global_load_dwordx2 v[194:195], v4, s[6:7] offset:2048 nt
	global_load_dwordx2 v[192:193], v4, s[6:7] offset:2560 nt
	global_load_dwordx2 v[188:189], v4, s[6:7] offset:3072 nt
	global_load_dwordx2 v[186:187], v4, s[6:7] offset:3584 nt
	v_addc_co_u32_e32 v7, vcc, 0, v7, vcc
	global_load_dwordx2 v[184:185], v[6:7], off nt
	global_load_dwordx2 v[182:183], v[6:7], off offset:512 nt
	global_load_dwordx2 v[178:179], v[6:7], off offset:1024 nt
	global_load_dwordx2 v[176:177], v[6:7], off offset:1536 nt
	global_load_dwordx2 v[174:175], v[6:7], off offset:2048 nt
	global_load_dwordx2 v[172:173], v[6:7], off offset:2560 nt
	global_load_dwordx2 v[170:171], v[6:7], off offset:3072 nt
	global_load_dwordx2 v[168:169], v[6:7], off offset:3584 nt
	s_add_u32 s0, s24, s0
	s_addc_u32 s1, s25, s1
	v_lshl_add_u64 v[130:131], s[52:53], 0, v[2:3]
	v_add_u32_e32 v1, 0, v2
	v_lshl_add_u64 v[2:3], s[0:1], 0, v[4:5]
	s_mov_b64 s[0:1], 0x1a900000
	v_lshl_add_u64 v[134:135], v[2:3], 0, s[0:1]
	s_ashr_i32 s49, s48, 31
	v_mbcnt_lo_u32_b32 v2, -1, 0
	v_lshl_add_u64 v[132:133], s[50:51], 0, v[4:5]
	s_lshl_b64 s[6:7], s[48:49], 13
	s_mov_b32 s13, 0x8400000
	s_mov_b32 s15, 0x8401000
	v_mov_b32_e32 v202, 0x358637bd
	s_mov_b32 s16, 0xf800000
	v_mov_b32_e32 v203, 0x260
	v_mbcnt_hi_u32_b32 v204, -1, v2
	s_branch .LBB0_924

; #define GAS __attribute__((address_space(1)))
; __device__ __forceinline__ void norm_phase(const Args& a, LAS unsigned char* lds, int layer, const float* xlat, const float* xctx, int nrows, const bf16* yadd, bf16* xout) {
;     ...
;     auto loadrow = [&](int row, f32x4 (&dst)[16], v2u (&yd)[16]) {
;         const float* xr = (row < MLAT) ? xlat + (size_t)row * D : xctx + (size_t)(row - MLAT) * D;
;         const GAS f32x4* xp = (const GAS f32x4*)xr + lane;
; #pragma unroll
;         for (int q = 0; q < 16; ++q) dst[q] = xp[64 * q];
;         if (yadd) { const GAS v2u* yp = (const GAS v2u*)(yadd + (size_t)row * D) + lane;
; #pragma unroll
;             for (int q = 0; q < 16; ++q) yd[q] = yp[64 * q]; }
;     };
;     int row = gw;
;     if (row < nrows) loadrow(row, v, yv);
;     while (row < nrows) {
;         const int nrow = row + NGW;
;         if (nrow < nrows) loadrow(nrow, vn, yn);
.LBB0_924:
	s_add_i32 s8, s12, s48
	s_cmpk_gt_i32 s8, 0x3fff
	s_cselect_b64 s[10:11], -1, 0
	s_and_b64 vcc, exec, s[10:11]
	s_cbranch_vccnz .LBB0_923
	s_ashr_i32 s9, s8, 31
	s_lshl_b64 s[0:1], s[8:9], 14
	v_lshl_add_u64 v[50:51], v[130:131], 0, s[0:1]
	v_add_co_u32_e32 v18, vcc, 0x1000, v50
	global_load_dwordx4 v[14:17], v[50:51], off nt
	global_load_dwordx4 v[10:13], v[50:51], off offset:1024 nt
	global_load_dwordx4 v[6:9], v[50:51], off offset:2048 nt
	global_load_dwordx4 v[2:5], v[50:51], off offset:3072 nt
	v_addc_co_u32_e32 v19, vcc, 0, v51, vcc
	v_add_co_u32_e32 v34, vcc, 0x2000, v50
	s_lshl_b64 s[0:1], s[8:9], 13
	s_nop 0
	v_addc_co_u32_e32 v35, vcc, 0, v51, vcc
	v_add_co_u32_e32 v50, vcc, 0x3000, v50
	v_lshl_add_u64 v[152:153], v[132:133], 0, s[0:1]
	s_nop 0
	v_addc_co_u32_e32 v51, vcc, 0, v51, vcc
	global_load_dwordx4 v[30:33], v[18:19], off nt
	global_load_dwordx4 v[26:29], v[18:19], off offset:1024 nt
	global_load_dwordx4 v[22:25], v[18:19], off offset:2048 nt
	s_nop 0
	global_load_dwordx4 v[18:21], v[18:19], off offset:3072 nt
	s_nop 0
	global_load_dwordx4 v[46:49], v[34:35], off nt
	global_load_dwordx4 v[42:45], v[34:35], off offset:1024 nt
	global_load_dwordx4 v[38:41], v[34:35], off offset:2048 nt
	s_nop 0
	global_load_dwordx4 v[34:37], v[34:35], off offset:3072 nt
	s_nop 0
	global_load_dwordx4 v[62:65], v[50:51], off nt
	global_load_dwordx4 v[58:61], v[50:51], off offset:1024 nt
	global_load_dwordx4 v[54:57], v[50:51], off offset:2048 nt
	s_nop 0
	global_load_dwordx4 v[50:53], v[50:51], off offset:3072 nt
	s_nop 0
	global_load_dwordx2 v[150:151], v[152:153], off nt
	global_load_dwordx2 v[148:149], v[152:153], off offset:512 nt
	global_load_dwordx2 v[146:147], v[152:153], off offset:1024 nt
	global_load_dwordx2 v[144:145], v[152:153], off offset:1536 nt
	global_load_dwordx2 v[142:143], v[152:153], off offset:2048 nt
	global_load_dwordx2 v[140:141], v[152:153], off offset:2560 nt
	global_load_dwordx2 v[138:139], v[152:153], off offset:3072 nt
	global_load_dwordx2 v[136:137], v[152:153], off offset:3584 nt
	v_add_co_u32_e32 v152, vcc, 0x1000, v152
	s_nop 1
	v_addc_co_u32_e32 v153, vcc, 0, v153, vcc
	global_load_dwordx2 v[166:167], v[152:153], off nt
	global_load_dwordx2 v[164:165], v[152:153], off offset:512 nt
	global_load_dwordx2 v[162:163], v[152:153], off offset:1024 nt
	global_load_dwordx2 v[160:161], v[152:153], off offset:1536 nt
	global_load_dwordx2 v[158:159], v[152:153], off offset:2048 nt
	global_load_dwordx2 v[156:157], v[152:153], off offset:2560 nt
	global_load_dwordx2 v[154:155], v[152:153], off offset:3072 nt
	s_nop 0
	global_load_dwordx2 v[152:153], v[152:153], off offset:3584 nt
	s_branch .LBB0_923

; #define GAS __attribute__((address_space(1)))
; __device__ __forceinline__ int my_tid() { int t = threadIdx.x; asm volatile("" : "+v"(t)); return t; }
; __global__ void __launch_bounds__(NTHREADS, 2) fwd(Args a) {
;     ...
;     if (IN(13)) {
;         const int tid = my_tid(), lane = tid & 63, gw = bx * NWAVES + __builtin_amdgcn_readfirstlane(tid >> 6);
;         const float* fg = a.in[I_FING]; const bf16* X1 = (const bf16*)(ws + WS_X1); const bf16* Y1 = (const bf16*)(ws + WS_Y1);
;         f32x4 v[16]; v2u xv[16], xn[16], yv[16], yn[16];
;         auto loadrow = [&](int row, v2u (&dst)[16], v2u (&yd)[16]) {
;             const GAS v2u* xp = (const GAS v2u*)(X1 + (size_t)row * D) + lane; const GAS v2u* yp = (const GAS v2u*)(Y1 + (size_t)row * D) + lane;
; #pragma unroll
;             for (int q = 0; q < 16; ++q) { dst[q] = xp[64 * q]; yd[q] = yp[64 * q]; }
;         };
;         int row = gw;
;         if (row < MLAT) loadrow(row, xv, yv);
;         while (row < MLAT) {
;             const int nrow = row + NGW;
;             if (nrow < MLAT) loadrow(nrow, xn, yn);
;             GAS f32x4* op = (GAS f32x4*)(a.out + (size_t)row * D) + lane;
;             float s = 0.f;
; #pragma unroll
;             for (int q = 0; q < 16; ++q) { v[q] = (f32x4){bflo(xv[q].x), bfhi(xv[q].x), bflo(xv[q].y), bfhi(xv[q].y)} + (f32x4){bflo(yv[q].x), bfhi(yv[q].x), bflo(yv[q].y), bfhi(yv[q].y)}; s += (v[q].x * v[q].x + v[q].y * v[q].y) + (v[q].z * v[q].z + v[q].w * v[q].w); }
;             const float rstd = 1.0f / sqrtf(wave_sum(s) * (1.0f / D) + 1e-6f);
; #pragma unroll
;             for (int q = 0; q < 16; ++q) { const f32x4 gg = *(const GAS f32x4*)(fg + 4 * lane + 256 * q); op[64 * q] = v[q] * rstd * gg; }
.LBB0_1268:
	s_cmp_lt_i32 s26, 14
	s_cselect_b64 s[0:1], -1, 0
	s_and_b64 s[0:1], s[0:1], s[2:3]
	s_andn2_b64 vcc, exec, s[0:1]
	s_cbranch_vccnz .LBB0_1274
	s_nop 0
	v_readfirstlane_b32 s0, v0
	s_ashr_i32 s0, s0, 6
	s_add_i32 s2, s0, s33
	s_cmpk_gt_i32 s2, 0x3fff
	s_cbranch_scc1 .LBB0_1274
	s_ashr_i32 s3, s2, 31
	s_lshl_b64 s[4:5], s[2:3], 13
	s_waitcnt vmcnt(0)
	v_and_b32_e32 v6, 63, v0
	s_add_u32 s6, s24, s4
	s_addc_u32 s7, s25, s5
	v_lshlrev_b32_e32 v28, 3, v6
	v_mov_b32_e32 v29, 0
	v_lshl_add_u64 v[0:1], s[6:7], 0, v[28:29]
	s_mov_b64 s[6:7], 0x22d00000
	s_add_u32 s4, s50, s4
	s_mov_b32 s1, 0x22d01000
	v_lshl_add_u64 v[2:3], v[0:1], 0, s[6:7]
	s_addc_u32 s5, s51, s5
	v_add_co_u32_e32 v0, vcc, s1, v0
	v_lshl_add_u64 v[4:5], s[4:5], 0, v[28:29]
	s_nop 0
	v_addc_co_u32_e32 v1, vcc, 0, v1, vcc
	s_movk_i32 s3, 0x1000
	v_add_co_u32_e32 v4, vcc, s3, v4
	global_load_dwordx2 v[148:149], v[2:3], off offset:512 nt
	global_load_dwordx2 v[144:145], v[2:3], off offset:1024 nt
	global_load_dwordx2 v[142:143], v[2:3], off offset:1536 nt
	global_load_dwordx2 v[136:137], v[2:3], off offset:2048 nt
	global_load_dwordx2 v[156:157], v28, s[4:5] offset:512 nt
	global_load_dwordx2 v[150:151], v28, s[4:5] offset:1024 nt
	global_load_dwordx2 v[146:147], v28, s[4:5] offset:1536 nt
	global_load_dwordx2 v[140:141], v28, s[4:5] offset:2048 nt
	global_load_dwordx2 v[152:153], v[0:1], off offset:-4096 nt
	global_load_dwordx2 v[138:139], v28, s[4:5] offset:2560 nt
	global_load_dwordx2 v[134:135], v28, s[4:5] offset:3072 nt
	global_load_dwordx2 v[128:129], v28, s[4:5] offset:3584 nt
	v_addc_co_u32_e32 v5, vcc, 0, v5, vcc
	global_load_dwordx2 v[132:133], v[2:3], off offset:2560 nt
	global_load_dwordx2 v[130:131], v[2:3], off offset:3072 nt
	global_load_dwordx2 v[124:125], v[2:3], off offset:3584 nt
	global_load_dwordx2 v[126:127], v[4:5], off nt
	global_load_dwordx2 v[120:121], v[0:1], off nt
	global_load_dwordx2 v[118:119], v[0:1], off offset:512 nt
	global_load_dwordx2 v[112:113], v[0:1], off offset:1024 nt
	global_load_dwordx2 v[108:109], v[0:1], off offset:1536 nt
	global_load_dwordx2 v[122:123], v[4:5], off offset:512 nt
	global_load_dwordx2 v[116:117], v[4:5], off offset:1024 nt
	global_load_dwordx2 v[114:115], v[4:5], off offset:1536 nt
	global_load_dwordx2 v[110:111], v[4:5], off offset:2048 nt
	global_load_dwordx2 v[106:107], v[0:1], off offset:2048 nt
	global_load_dwordx2 v[100:101], v[0:1], off offset:2560 nt
	global_load_dwordx2 v[96:97], v[0:1], off offset:3072 nt
	global_load_dwordx2 v[94:95], v[0:1], off offset:3584 nt
	global_load_dwordx2 v[154:155], v28, s[4:5] nt
	global_load_dwordx2 v[104:105], v[4:5], off offset:2560 nt
	global_load_dwordx2 v[102:103], v[4:5], off offset:3072 nt
	global_load_dwordx2 v[98:99], v[4:5], off offset:3584 nt
	v_mbcnt_lo_u32_b32 v0, -1, 0
	v_mbcnt_hi_u32_b32 v0, -1, v0
	v_and_b32_e32 v1, 64, v0
	v_add_u32_e32 v1, 64, v1
	v_xor_b32_e32 v2, 1, v0
	v_cmp_lt_i32_e32 vcc, v2, v1
	v_lshlrev_b32_e32 v26, 4, v6
	v_mov_b32_e32 v27, v29
	v_cndmask_b32_e32 v2, v0, v2, vcc
	v_lshlrev_b32_e32 v165, 2, v2
	v_xor_b32_e32 v2, 2, v0
	v_cmp_lt_i32_e32 vcc, v2, v1
	s_mov_b64 s[4:5], 0x1000
	s_ashr_i32 s1, s0, 31
	v_cndmask_b32_e32 v2, v0, v2, vcc
	v_lshlrev_b32_e32 v166, 2, v2
	v_xor_b32_e32 v2, 4, v0
	v_cmp_lt_i32_e32 vcc, v2, v1
	s_mov_b32 s10, 0xe0300000
	v_mov_b32_e32 v171, 0x358637bd
	v_cndmask_b32_e32 v2, v0, v2, vcc
	v_lshlrev_b32_e32 v167, 2, v2
	v_xor_b32_e32 v2, 8, v0
	v_cmp_lt_i32_e32 vcc, v2, v1
	s_mov_b32 s11, 0xf800000
	v_mov_b32_e32 v172, 0x260
	v_cndmask_b32_e32 v2, v0, v2, vcc
	v_lshlrev_b32_e32 v168, 2, v2
	v_xor_b32_e32 v2, 16, v0
	v_cmp_lt_i32_e32 vcc, v2, v1
	s_movk_i32 s12, 0x2000
	s_movk_i32 s13, 0x3000
	v_cndmask_b32_e32 v2, v0, v2, vcc
	v_lshlrev_b32_e32 v169, 2, v2
	v_xor_b32_e32 v2, 32, v0
	v_cmp_lt_i32_e32 vcc, v2, v1
	s_nop 1
	v_cndmask_b32_e32 v0, v0, v2, vcc
	v_lshlrev_b32_e32 v170, 2, v0
	v_lshl_add_u64 v[0:1], s[72:73], 0, v[26:27]
	v_lshl_add_u64 v[2:3], v[0:1], 0, s[4:5]
	s_mov_b64 s[4:5], 0x1400
	v_lshl_add_u64 v[4:5], v[0:1], 0, s[4:5]
	s_mov_b64 s[4:5], 0x1800
	s_waitcnt lgkmcnt(0)
	v_lshl_add_u64 v[6:7], v[0:1], 0, s[4:5]
	s_mov_b64 s[4:5], 0x1c00
	v_lshl_add_u64 v[8:9], v[0:1], 0, s[4:5]
	s_mov_b64 s[4:5], 0x2000
	v_lshl_add_u64 v[10:11], v[0:1], 0, s[4:5]
	s_mov_b64 s[4:5], 0x2400
	v_lshl_add_u64 v[12:13], v[0:1], 0, s[4:5]
	s_mov_b64 s[4:5], 0x2800
	v_lshl_add_u64 v[14:15], v[0:1], 0, s[4:5]
	s_mov_b64 s[4:5], 0x2c00
	v_lshl_add_u64 v[16:17], v[0:1], 0, s[4:5]
	s_mov_b64 s[4:5], 0x3000
	v_lshl_add_u64 v[18:19], v[0:1], 0, s[4:5]
	s_mov_b64 s[4:5], 0x3400
	v_lshl_add_u64 v[20:21], v[0:1], 0, s[4:5]
	s_mov_b64 s[4:5], 0x3800
	v_lshl_add_u64 v[22:23], v[0:1], 0, s[4:5]
	s_mov_b64 s[4:5], 0x3c00
	v_lshl_add_u64 v[24:25], v[0:1], 0, s[4:5]
	s_ashr_i32 s4, s33, 31
	s_add_u32 s0, s0, s33
	s_addc_u32 s1, s1, s4
	s_lshl_b64 s[0:1], s[0:1], 14
	s_add_u32 s0, s74, s0
	s_addc_u32 s1, s75, s1
	v_lshl_add_u64 v[26:27], s[0:1], 0, v[26:27]
	s_add_i32 s0, s2, s48
	s_ashr_i32 s49, s48, 31
	s_ashr_i32 s1, s0, 31
	s_lshl_b64 s[4:5], s[48:49], 14
	s_lshl_b64 s[0:1], s[0:1], 13
	s_add_u32 s0, s24, s0
	s_addc_u32 s1, s25, s1
	v_lshl_add_u64 v[28:29], s[0:1], 0, v[28:29]
	s_mov_b64 s[0:1], 0x42a01e00
	v_lshl_add_u64 v[28:29], v[28:29], 0, s[0:1]
	s_lshl_b64 s[6:7], s[48:49], 13
	s_branch .LBB0_1272

; #define GAS __attribute__((address_space(1)))
; __global__ void __launch_bounds__(NTHREADS, 2) fwd(Args a) {
;     ...
;         auto loadrow = [&](int row, v2u (&dst)[16], v2u (&yd)[16]) {
;             const GAS v2u* xp = (const GAS v2u*)(X1 + (size_t)row * D) + lane; const GAS v2u* yp = (const GAS v2u*)(Y1 + (size_t)row * D) + lane;
; #pragma unroll
;             for (int q = 0; q < 16; ++q) { dst[q] = xp[64 * q]; yd[q] = yp[64 * q]; }
;         };
;         int row = gw;
;         if (row < MLAT) loadrow(row, xv, yv);
;         while (row < MLAT) {
;             const int nrow = row + NGW;
;             if (nrow < MLAT) loadrow(nrow, xn, yn);
.LBB0_1272:
	s_add_i32 s2, s2, s48
	s_cmpk_gt_i32 s2, 0x3fff
	s_cselect_b64 s[8:9], -1, 0
	s_and_b64 vcc, exec, s[8:9]
	s_cbranch_vccnz .LBB0_1271
	v_add_co_u32_e32 v44, vcc, 0xe02ff000, v28
	s_nop 1
	v_addc_co_u32_e32 v45, vcc, -1, v29, vcc
	v_add_co_u32_e32 v46, vcc, 0xfffff000, v28
	s_nop 1
	v_addc_co_u32_e32 v47, vcc, -1, v29, vcc
	v_add_co_u32_e32 v60, vcc, s10, v28
	global_load_dwordx2 v[30:31], v[44:45], off offset:-3584 nt
	global_load_dwordx2 v[32:33], v[44:45], off offset:-3072 nt
	global_load_dwordx2 v[34:35], v[44:45], off offset:-2560 nt
	global_load_dwordx2 v[36:37], v[44:45], off offset:-2048 nt
	global_load_dwordx2 v[68:69], v[46:47], off offset:-3584 nt
	global_load_dwordx2 v[66:67], v[46:47], off offset:-3072 nt
	global_load_dwordx2 v[64:65], v[46:47], off offset:-2560 nt
	global_load_dwordx2 v[62:63], v[46:47], off offset:-2048 nt
	global_load_dwordx2 v[38:39], v[44:45], off offset:-1536 nt
	global_load_dwordx2 v[40:41], v[44:45], off offset:-1024 nt
	global_load_dwordx2 v[42:43], v[44:45], off offset:-512 nt
	s_nop 0
	global_load_dwordx2 v[44:45], v[44:45], off nt
	v_addc_co_u32_e32 v61, vcc, -1, v29, vcc
	global_load_dwordx2 v[74:75], v[46:47], off offset:-1536 nt
	global_load_dwordx2 v[72:73], v[46:47], off offset:-1024 nt
	global_load_dwordx2 v[70:71], v[46:47], off offset:-512 nt
	s_nop 0
	global_load_dwordx2 v[46:47], v[60:61], off offset:-3584 nt
	global_load_dwordx2 v[76:77], v[28:29], off offset:-3584 nt
	global_load_dwordx2 v[78:79], v[28:29], off offset:-3072 nt
	global_load_dwordx2 v[80:81], v[28:29], off offset:-2560 nt
	global_load_dwordx2 v[82:83], v[28:29], off offset:-2048 nt
	global_load_dwordx2 v[54:55], v[60:61], off offset:-3072 nt
	global_load_dwordx2 v[52:53], v[60:61], off offset:-2560 nt
	global_load_dwordx2 v[50:51], v[60:61], off offset:-2048 nt
	global_load_dwordx2 v[48:49], v[60:61], off offset:-1536 nt
	global_load_dwordx2 v[84:85], v[28:29], off offset:-4096 nt
	global_load_dwordx2 v[56:57], v[60:61], off offset:-1024 nt
	global_load_dwordx2 v[58:59], v[60:61], off offset:-512 nt
	s_nop 0
	global_load_dwordx2 v[60:61], v[60:61], off nt
	s_nop 0
	global_load_dwordx2 v[92:93], v[28:29], off offset:-1536 nt
	global_load_dwordx2 v[90:91], v[28:29], off offset:-1024 nt
	global_load_dwordx2 v[88:89], v[28:29], off offset:-512 nt
	global_load_dwordx2 v[86:87], v[28:29], off nt
	s_branch .LBB0_1271
